# all nine GEMM K-loops: early wave group's vmcnt(8) moved from the end of its load cluster to the end of its MFMA cluster
# baseline (speedup 1.0000x reference)
.LBB0_251:
	ds_read_b128 v[130:133], v158
	ds_read_b128 v[134:137], v158 offset:1024
	ds_read_b128 v[138:141], v158 offset:2048
	ds_read_b128 v[142:145], v158 offset:3072
	ds_read_b128 v[146:149], v159
	ds_read_b128 v[162:165], v159 offset:1024
	ds_read_b128 v[166:169], v159 offset:2048
	ds_read_b128 v[170:173], v159 offset:3072
	s_add_u32 s10, s8, 0xfff80080
	s_addc_u32 s11, s9, -1
	s_cmp_eq_u32 s45, 28
	s_cselect_b32 s11, s37, s11
	s_cselect_b32 s10, s36, s10
	s_cselect_b32 s43, s39, s35
	s_cselect_b32 s42, s38, s7
	v_mov_b32_e32 v128, v153
	v_mov_b32_e32 v150, v154
	s_add_i32 m0, s52, 0xc000
	ds_read_b128 v[174:177], v160
	ds_read_b128 v[178:181], v160 offset:1024
	ds_read_b128 v[182:185], v160 offset:2048
	ds_read_b128 v[186:189], v160 offset:3072
	ds_read_b128 v[190:193], v160 offset:4096
	ds_read_b128 v[194:197], v160 offset:5120
	ds_read_b128 v[198:201], v160 offset:6144
	ds_read_b128 v[202:205], v160 offset:7168
	s_nop 0
	global_load_lds_dwordx4 v128, s[8:9]
	s_add_i32 m0, s52, 0xe000
	s_nop 0
	global_load_lds_dwordx4 v150, s[8:9]
	s_and_b64 vcc, exec, s[22:23]
	s_cbranch_vccnz .Lmy_lw_1
	s_waitcnt vmcnt(8)
.Lmy_lw_1:
	s_waitcnt lgkmcnt(0)
	s_barrier
	s_setprio 1
	s_waitcnt lgkmcnt(0)
	v_mfma_f32_16x16x32_bf16 v[124:127], v[130:133], v[174:177], v[124:127]
	v_mfma_f32_16x16x32_bf16 v[120:123], v[138:141], v[174:177], v[120:123]
	v_mfma_f32_16x16x32_bf16 v[108:111], v[130:133], v[182:185], v[108:111]
	v_mfma_f32_16x16x32_bf16 v[104:107], v[138:141], v[182:185], v[104:107]
	v_mfma_f32_16x16x32_bf16 v[92:95], v[130:133], v[190:193], v[92:95]
	v_mfma_f32_16x16x32_bf16 v[88:91], v[138:141], v[190:193], v[88:91]
	v_mfma_f32_16x16x32_bf16 v[76:79], v[130:133], v[198:201], v[76:79]
	v_mfma_f32_16x16x32_bf16 v[72:75], v[138:141], v[198:201], v[72:75]
	v_mfma_f32_16x16x32_bf16 v[124:127], v[134:137], v[178:181], v[124:127]
	v_mfma_f32_16x16x32_bf16 v[120:123], v[142:145], v[178:181], v[120:123]
	v_mfma_f32_16x16x32_bf16 v[108:111], v[134:137], v[186:189], v[108:111]
	v_mfma_f32_16x16x32_bf16 v[104:107], v[142:145], v[186:189], v[104:107]
	v_mfma_f32_16x16x32_bf16 v[92:95], v[134:137], v[194:197], v[92:95]
	v_mfma_f32_16x16x32_bf16 v[88:91], v[142:145], v[194:197], v[88:91]
	v_mfma_f32_16x16x32_bf16 v[76:79], v[134:137], v[202:205], v[76:79]
	v_mfma_f32_16x16x32_bf16 v[72:75], v[142:145], v[202:205], v[72:75]
	s_setprio 0
	s_setprio 1
	v_mfma_f32_16x16x32_bf16 v[116:119], v[146:149], v[174:177], v[116:119]
	v_mfma_f32_16x16x32_bf16 v[112:115], v[166:169], v[174:177], v[112:115]
	v_mfma_f32_16x16x32_bf16 v[100:103], v[146:149], v[182:185], v[100:103]
	v_mfma_f32_16x16x32_bf16 v[96:99], v[166:169], v[182:185], v[96:99]
	v_mfma_f32_16x16x32_bf16 v[84:87], v[146:149], v[190:193], v[84:87]
	v_mfma_f32_16x16x32_bf16 v[80:83], v[166:169], v[190:193], v[80:83]
	v_mfma_f32_16x16x32_bf16 v[68:71], v[146:149], v[198:201], v[68:71]
	v_mfma_f32_16x16x32_bf16 v[64:67], v[166:169], v[198:201], v[64:67]
	v_mfma_f32_16x16x32_bf16 v[116:119], v[162:165], v[178:181], v[116:119]
	v_mfma_f32_16x16x32_bf16 v[112:115], v[170:173], v[178:181], v[112:115]
	v_mfma_f32_16x16x32_bf16 v[100:103], v[162:165], v[186:189], v[100:103]
	v_mfma_f32_16x16x32_bf16 v[96:99], v[170:173], v[186:189], v[96:99]
	v_mfma_f32_16x16x32_bf16 v[84:87], v[162:165], v[194:197], v[84:87]
	v_mfma_f32_16x16x32_bf16 v[80:83], v[170:173], v[194:197], v[80:83]
	v_mfma_f32_16x16x32_bf16 v[68:71], v[162:165], v[202:205], v[68:71]
	v_mfma_f32_16x16x32_bf16 v[64:67], v[170:173], v[202:205], v[64:67]
	s_setprio 0
	s_waitcnt vmcnt(8)
	s_barrier
	s_add_i32 s46, s74, s3
	v_mov_b32_e32 v128, v155
	v_mov_b32_e32 v150, v156
	s_mov_b32 m0, s46
	ds_read_b128 v[174:177], v160 offset:16384
	ds_read_b128 v[178:181], v160 offset:17408
	ds_read_b128 v[182:185], v160 offset:18432
	ds_read_b128 v[186:189], v160 offset:19456
	ds_read_b128 v[190:193], v160 offset:20480
	ds_read_b128 v[194:197], v160 offset:21504
	ds_read_b128 v[198:201], v160 offset:22528
	ds_read_b128 v[202:205], v160 offset:23552
	s_nop 0
	global_load_lds_dwordx4 v128, s[42:43]
	s_add_i32 m0, s46, 0x2000
	s_add_u32 s46, s42, 0x80000
	s_addc_u32 s47, s43, 0
	s_add_i32 s48, s75, s3
	global_load_lds_dwordx4 v150, s[42:43]
	v_mov_b32_e32 v128, v155
	v_mov_b32_e32 v150, v156
	s_mov_b32 m0, s48
	s_nop 0
	global_load_lds_dwordx4 v128, s[46:47]
	s_add_i32 m0, s48, 0x2000
	v_mov_b32_e32 v128, v153
	global_load_lds_dwordx4 v150, s[46:47]
	v_mov_b32_e32 v150, v154
	s_mov_b32 m0, s52
	s_nop 0
	global_load_lds_dwordx4 v128, s[10:11]
	s_mov_b32 m0, s53
	s_nop 0
	global_load_lds_dwordx4 v150, s[10:11]
	s_and_b64 vcc, exec, s[22:23]
	s_cbranch_vccnz .Lmy_lw_2
	s_waitcnt vmcnt(8)
.Lmy_lw_2:
	s_waitcnt lgkmcnt(0)
	s_barrier
	s_setprio 1
	s_waitcnt lgkmcnt(0)
	v_mfma_f32_16x16x32_bf16 v[60:63], v[130:133], v[174:177], v[60:63]
	v_mfma_f32_16x16x32_bf16 v[56:59], v[138:141], v[174:177], v[56:59]
	v_mfma_f32_16x16x32_bf16 v[44:47], v[130:133], v[182:185], v[44:47]
	v_mfma_f32_16x16x32_bf16 v[40:43], v[138:141], v[182:185], v[40:43]
	v_mfma_f32_16x16x32_bf16 v[28:31], v[130:133], v[190:193], v[28:31]
	v_mfma_f32_16x16x32_bf16 v[24:27], v[138:141], v[190:193], v[24:27]
	v_mfma_f32_16x16x32_bf16 v[12:15], v[130:133], v[198:201], v[12:15]
	v_mfma_f32_16x16x32_bf16 v[8:11], v[138:141], v[198:201], v[8:11]
	v_mfma_f32_16x16x32_bf16 v[60:63], v[134:137], v[178:181], v[60:63]
	v_mfma_f32_16x16x32_bf16 v[56:59], v[142:145], v[178:181], v[56:59]
	v_mfma_f32_16x16x32_bf16 v[44:47], v[134:137], v[186:189], v[44:47]
	v_mfma_f32_16x16x32_bf16 v[40:43], v[142:145], v[186:189], v[40:43]
	v_mfma_f32_16x16x32_bf16 v[28:31], v[134:137], v[194:197], v[28:31]
	v_mfma_f32_16x16x32_bf16 v[24:27], v[142:145], v[194:197], v[24:27]
	v_mfma_f32_16x16x32_bf16 v[12:15], v[134:137], v[202:205], v[12:15]
	v_mfma_f32_16x16x32_bf16 v[8:11], v[142:145], v[202:205], v[8:11]
	s_setprio 0
	s_setprio 1
	v_mfma_f32_16x16x32_bf16 v[52:55], v[146:149], v[174:177], v[52:55]
	v_mfma_f32_16x16x32_bf16 v[48:51], v[166:169], v[174:177], v[48:51]
	v_mfma_f32_16x16x32_bf16 v[36:39], v[146:149], v[182:185], v[36:39]
	v_mfma_f32_16x16x32_bf16 v[32:35], v[166:169], v[182:185], v[32:35]
	v_mfma_f32_16x16x32_bf16 v[20:23], v[146:149], v[190:193], v[20:23]
	v_mfma_f32_16x16x32_bf16 v[16:19], v[166:169], v[190:193], v[16:19]
	v_mfma_f32_16x16x32_bf16 v[4:7], v[146:149], v[198:201], v[4:7]
	v_mfma_f32_16x16x32_bf16 v[0:3], v[166:169], v[198:201], v[0:3]
	v_mfma_f32_16x16x32_bf16 v[52:55], v[162:165], v[178:181], v[52:55]
	v_mfma_f32_16x16x32_bf16 v[48:51], v[170:173], v[178:181], v[48:51]
	v_mfma_f32_16x16x32_bf16 v[36:39], v[162:165], v[186:189], v[36:39]
	v_mfma_f32_16x16x32_bf16 v[32:35], v[170:173], v[186:189], v[32:35]
	v_mfma_f32_16x16x32_bf16 v[20:23], v[162:165], v[194:197], v[20:23]
	v_mfma_f32_16x16x32_bf16 v[16:19], v[170:173], v[194:197], v[16:19]
	v_mfma_f32_16x16x32_bf16 v[4:7], v[162:165], v[202:205], v[4:7]
	v_mfma_f32_16x16x32_bf16 v[0:3], v[170:173], v[202:205], v[0:3]
	s_setprio 0
	s_waitcnt vmcnt(8)
	s_barrier
	s_add_i32 s48, 0, 0x18000
	v_add_u32_e32 v128, s48, v157
	s_add_i32 s49, 0, 0x1c000
	ds_read_b128 v[130:133], v128
	ds_read_b128 v[134:137], v128 offset:1024
	ds_read_b128 v[138:141], v128 offset:2048
	ds_read_b128 v[142:145], v128 offset:3072
	v_add_u32_e32 v128, s49, v157
	ds_read_b128 v[146:149], v128
	ds_read_b128 v[162:165], v128 offset:1024
	ds_read_b128 v[166:169], v128 offset:2048
	ds_read_b128 v[170:173], v128 offset:3072
	s_add_u32 s46, s10, 0x80000
	v_mov_b32_e32 v128, v153
	v_mov_b32_e32 v150, v154
	s_addc_u32 s47, s11, 0
	s_mov_b32 m0, s54
	ds_read_b128 v[174:177], v160 offset:32768
	ds_read_b128 v[178:181], v160 offset:33792
	ds_read_b128 v[182:185], v160 offset:34816
	ds_read_b128 v[186:189], v160 offset:35840
	ds_read_b128 v[190:193], v160 offset:36864
	ds_read_b128 v[194:197], v160 offset:37888
	ds_read_b128 v[198:201], v160 offset:38912
	ds_read_b128 v[202:205], v160 offset:39936
	s_nop 0
	global_load_lds_dwordx4 v128, s[46:47]
	s_mov_b32 m0, s55
	s_nop 0
	global_load_lds_dwordx4 v150, s[46:47]
	s_and_b64 vcc, exec, s[22:23]
	s_cbranch_vccnz .Lmy_lw_3
	s_waitcnt vmcnt(8)
.Lmy_lw_3:
	s_waitcnt lgkmcnt(0)
	s_barrier
	s_setprio 1
	s_waitcnt lgkmcnt(0)
	v_mfma_f32_16x16x32_bf16 v[124:127], v[130:133], v[174:177], v[124:127]
	v_mfma_f32_16x16x32_bf16 v[120:123], v[138:141], v[174:177], v[120:123]
	v_mfma_f32_16x16x32_bf16 v[108:111], v[130:133], v[182:185], v[108:111]
	v_mfma_f32_16x16x32_bf16 v[104:107], v[138:141], v[182:185], v[104:107]
	v_mfma_f32_16x16x32_bf16 v[92:95], v[130:133], v[190:193], v[92:95]
	v_mfma_f32_16x16x32_bf16 v[88:91], v[138:141], v[190:193], v[88:91]
	v_mfma_f32_16x16x32_bf16 v[76:79], v[130:133], v[198:201], v[76:79]
	v_mfma_f32_16x16x32_bf16 v[72:75], v[138:141], v[198:201], v[72:75]
	v_mfma_f32_16x16x32_bf16 v[124:127], v[134:137], v[178:181], v[124:127]
	v_mfma_f32_16x16x32_bf16 v[120:123], v[142:145], v[178:181], v[120:123]
	v_mfma_f32_16x16x32_bf16 v[108:111], v[134:137], v[186:189], v[108:111]
	v_mfma_f32_16x16x32_bf16 v[104:107], v[142:145], v[186:189], v[104:107]
	v_mfma_f32_16x16x32_bf16 v[92:95], v[134:137], v[194:197], v[92:95]
	v_mfma_f32_16x16x32_bf16 v[88:91], v[142:145], v[194:197], v[88:91]
	v_mfma_f32_16x16x32_bf16 v[76:79], v[134:137], v[202:205], v[76:79]
	v_mfma_f32_16x16x32_bf16 v[72:75], v[142:145], v[202:205], v[72:75]
	s_setprio 0
	s_setprio 1
	v_mfma_f32_16x16x32_bf16 v[116:119], v[146:149], v[174:177], v[116:119]
	v_mfma_f32_16x16x32_bf16 v[112:115], v[166:169], v[174:177], v[112:115]
	v_mfma_f32_16x16x32_bf16 v[100:103], v[146:149], v[182:185], v[100:103]
	v_mfma_f32_16x16x32_bf16 v[96:99], v[166:169], v[182:185], v[96:99]
	v_mfma_f32_16x16x32_bf16 v[84:87], v[146:149], v[190:193], v[84:87]
	v_mfma_f32_16x16x32_bf16 v[80:83], v[166:169], v[190:193], v[80:83]
	v_mfma_f32_16x16x32_bf16 v[68:71], v[146:149], v[198:201], v[68:71]
	v_mfma_f32_16x16x32_bf16 v[64:67], v[166:169], v[198:201], v[64:67]
	v_mfma_f32_16x16x32_bf16 v[116:119], v[162:165], v[178:181], v[116:119]
	v_mfma_f32_16x16x32_bf16 v[112:115], v[170:173], v[178:181], v[112:115]
	v_mfma_f32_16x16x32_bf16 v[100:103], v[162:165], v[186:189], v[100:103]
	v_mfma_f32_16x16x32_bf16 v[96:99], v[170:173], v[186:189], v[96:99]
	v_mfma_f32_16x16x32_bf16 v[84:87], v[162:165], v[194:197], v[84:87]
	v_mfma_f32_16x16x32_bf16 v[80:83], v[170:173], v[194:197], v[80:83]
	v_mfma_f32_16x16x32_bf16 v[68:71], v[162:165], v[202:205], v[68:71]
	v_mfma_f32_16x16x32_bf16 v[64:67], v[170:173], v[202:205], v[64:67]
	s_setprio 0
	s_waitcnt vmcnt(8)
	s_barrier
	v_mov_b32_e32 v128, v155
	v_mov_b32_e32 v150, v156
	ds_read_b128 v[174:177], v160 offset:49152
	ds_read_b128 v[178:181], v160 offset:50176
	ds_read_b128 v[182:185], v160 offset:51200
	ds_read_b128 v[186:189], v160 offset:52224
	ds_read_b128 v[190:193], v160 offset:53248
	ds_read_b128 v[194:197], v160 offset:54272
	ds_read_b128 v[198:201], v160 offset:55296
	ds_read_b128 v[202:205], v160 offset:56320
	s_add_i32 s46, s48, s3
	v_lshl_add_u64 v[206:207], s[42:43], 0, v[128:129]
	v_lshl_add_u64 v[206:207], v[206:207], 0, s[20:21]
	s_mov_b32 m0, s46
	v_mov_b32_e32 v151, v129
	global_load_lds_dwordx4 v[206:207], off
	s_add_i32 m0, s46, 0x2000
	v_lshl_add_u64 v[150:151], s[42:43], 0, v[150:151]
	s_add_u32 s42, s42, 0x80080
	v_lshl_add_u64 v[150:151], v[150:151], 0, s[20:21]
	s_addc_u32 s43, s43, 0
	s_add_i32 s46, s49, s3
	global_load_lds_dwordx4 v[150:151], off
	v_mov_b32_e32 v128, v155
	v_mov_b32_e32 v150, v156
	s_mov_b32 m0, s46
	v_mov_b32_e32 v151, v129
	global_load_lds_dwordx4 v128, s[42:43]
	s_add_i32 m0, s46, 0x2000
	v_mov_b32_e32 v128, v153
	global_load_lds_dwordx4 v150, s[42:43]
	v_mov_b32_e32 v150, v154
	s_mov_b32 m0, s68
	v_lshl_add_u64 v[206:207], s[10:11], 0, v[128:129]
	v_lshl_add_u64 v[206:207], v[206:207], 0, s[20:21]
	v_lshl_add_u64 v[150:151], s[10:11], 0, v[150:151]
	global_load_lds_dwordx4 v[206:207], off
	v_lshl_add_u64 v[150:151], v[150:151], 0, s[20:21]
	s_mov_b32 m0, s69
	s_nop 0
	global_load_lds_dwordx4 v[150:151], off
	s_and_b64 vcc, exec, s[22:23]
	s_cbranch_vccnz .Lmy_lw_4
	s_waitcnt vmcnt(8)
.Lmy_lw_4:
	s_waitcnt lgkmcnt(0)
	s_barrier
	s_setprio 1
	s_waitcnt lgkmcnt(0)
	v_mfma_f32_16x16x32_bf16 v[60:63], v[130:133], v[174:177], v[60:63]
	v_mfma_f32_16x16x32_bf16 v[56:59], v[138:141], v[174:177], v[56:59]
	v_mfma_f32_16x16x32_bf16 v[44:47], v[130:133], v[182:185], v[44:47]
	v_mfma_f32_16x16x32_bf16 v[40:43], v[138:141], v[182:185], v[40:43]
	v_mfma_f32_16x16x32_bf16 v[28:31], v[130:133], v[190:193], v[28:31]
	v_mfma_f32_16x16x32_bf16 v[24:27], v[138:141], v[190:193], v[24:27]
	v_mfma_f32_16x16x32_bf16 v[12:15], v[130:133], v[198:201], v[12:15]
	v_mfma_f32_16x16x32_bf16 v[8:11], v[138:141], v[198:201], v[8:11]
	v_mfma_f32_16x16x32_bf16 v[60:63], v[134:137], v[178:181], v[60:63]
	v_mfma_f32_16x16x32_bf16 v[56:59], v[142:145], v[178:181], v[56:59]
	v_mfma_f32_16x16x32_bf16 v[44:47], v[134:137], v[186:189], v[44:47]
	v_mfma_f32_16x16x32_bf16 v[40:43], v[142:145], v[186:189], v[40:43]
	v_mfma_f32_16x16x32_bf16 v[28:31], v[134:137], v[194:197], v[28:31]
	v_mfma_f32_16x16x32_bf16 v[24:27], v[142:145], v[194:197], v[24:27]
	v_mfma_f32_16x16x32_bf16 v[12:15], v[134:137], v[202:205], v[12:15]
	v_mfma_f32_16x16x32_bf16 v[8:11], v[142:145], v[202:205], v[8:11]
	s_setprio 0
	s_setprio 1
	v_mfma_f32_16x16x32_bf16 v[52:55], v[146:149], v[174:177], v[52:55]
	v_mfma_f32_16x16x32_bf16 v[48:51], v[166:169], v[174:177], v[48:51]
	v_mfma_f32_16x16x32_bf16 v[36:39], v[146:149], v[182:185], v[36:39]
	v_mfma_f32_16x16x32_bf16 v[32:35], v[166:169], v[182:185], v[32:35]
	v_mfma_f32_16x16x32_bf16 v[20:23], v[146:149], v[190:193], v[20:23]
	v_mfma_f32_16x16x32_bf16 v[16:19], v[166:169], v[190:193], v[16:19]
	v_mfma_f32_16x16x32_bf16 v[4:7], v[146:149], v[198:201], v[4:7]
	v_mfma_f32_16x16x32_bf16 v[0:3], v[166:169], v[198:201], v[0:3]
	v_mfma_f32_16x16x32_bf16 v[52:55], v[162:165], v[178:181], v[52:55]
	v_mfma_f32_16x16x32_bf16 v[48:51], v[170:173], v[178:181], v[48:51]
	v_mfma_f32_16x16x32_bf16 v[36:39], v[162:165], v[186:189], v[36:39]
	v_mfma_f32_16x16x32_bf16 v[32:35], v[170:173], v[186:189], v[32:35]
	v_mfma_f32_16x16x32_bf16 v[20:23], v[162:165], v[194:197], v[20:23]
	v_mfma_f32_16x16x32_bf16 v[16:19], v[170:173], v[194:197], v[16:19]
	v_mfma_f32_16x16x32_bf16 v[4:7], v[162:165], v[202:205], v[4:7]
	v_mfma_f32_16x16x32_bf16 v[0:3], v[170:173], v[202:205], v[0:3]
	s_setprio 0
	s_waitcnt vmcnt(8)
	s_barrier
	s_add_i32 s45, s45, 2
	s_add_u32 s8, s8, 0x100
	s_addc_u32 s9, s9, 0
	s_add_u32 s7, s7, 0x100
	s_addc_u32 s35, s35, 0
	s_cmp_gt_u32 s45, 29
	s_cbranch_scc0 .LBB0_251
	s_and_b64 vcc, exec, s[22:23]
	s_cbranch_vccz .LBB0_254
	s_barrier

.LBB0_780:
	ds_read_b128 v[134:137], v150
	ds_read_b128 v[138:141], v150 offset:1024
	ds_read_b128 v[142:145], v150 offset:2048
	ds_read_b128 v[154:157], v150 offset:3072
	ds_read_b128 v[158:161], v151
	ds_read_b128 v[162:165], v151 offset:1024
	ds_read_b128 v[166:169], v151 offset:2048
	ds_read_b128 v[170:173], v151 offset:3072
	s_add_i32 s64, s44, 2
	s_add_u32 s46, s6, 0xfff90080
	s_addc_u32 s45, s7, -1
	s_cmp_eq_u32 s95, s44
	s_cselect_b32 s44, s89, s46
	s_cselect_b32 s45, s88, s45
	s_cselect_b32 s47, s93, s97
	s_cselect_b32 s46, s94, s96
	v_mov_b32_e32 v132, v128
	v_mov_b32_e32 v146, v130
	s_add_i32 m0, s37, 0xc000
	ds_read_b128 v[174:177], v152
	ds_read_b128 v[178:181], v152 offset:1024
	ds_read_b128 v[182:185], v152 offset:2048
	ds_read_b128 v[186:189], v152 offset:3072
	ds_read_b128 v[190:193], v152 offset:4096
	ds_read_b128 v[194:197], v152 offset:5120
	ds_read_b128 v[198:201], v152 offset:6144
	ds_read_b128 v[202:205], v152 offset:7168
	s_nop 0
	global_load_lds_dwordx4 v132, s[6:7]
	s_add_i32 m0, s37, 0xe000
	s_nop 0
	global_load_lds_dwordx4 v146, s[6:7]
	s_and_b64 vcc, exec, s[16:17]
	s_cbranch_vccnz .Lmy_lw_5
	s_waitcnt vmcnt(8)
.Lmy_lw_5:
	s_waitcnt lgkmcnt(0)
	s_barrier
	s_setprio 1
	s_waitcnt lgkmcnt(0)
	v_mfma_f32_16x16x32_bf16 v[124:127], v[134:137], v[174:177], v[124:127]
	v_mfma_f32_16x16x32_bf16 v[120:123], v[142:145], v[174:177], v[120:123]
	v_mfma_f32_16x16x32_bf16 v[108:111], v[134:137], v[182:185], v[108:111]
	v_mfma_f32_16x16x32_bf16 v[104:107], v[142:145], v[182:185], v[104:107]
	v_mfma_f32_16x16x32_bf16 v[92:95], v[134:137], v[190:193], v[92:95]
	v_mfma_f32_16x16x32_bf16 v[88:91], v[142:145], v[190:193], v[88:91]
	v_mfma_f32_16x16x32_bf16 v[76:79], v[134:137], v[198:201], v[76:79]
	v_mfma_f32_16x16x32_bf16 v[72:75], v[142:145], v[198:201], v[72:75]
	v_mfma_f32_16x16x32_bf16 v[124:127], v[138:141], v[178:181], v[124:127]
	v_mfma_f32_16x16x32_bf16 v[120:123], v[154:157], v[178:181], v[120:123]
	v_mfma_f32_16x16x32_bf16 v[108:111], v[138:141], v[186:189], v[108:111]
	v_mfma_f32_16x16x32_bf16 v[104:107], v[154:157], v[186:189], v[104:107]
	v_mfma_f32_16x16x32_bf16 v[92:95], v[138:141], v[194:197], v[92:95]
	v_mfma_f32_16x16x32_bf16 v[88:91], v[154:157], v[194:197], v[88:91]
	v_mfma_f32_16x16x32_bf16 v[76:79], v[138:141], v[202:205], v[76:79]
	v_mfma_f32_16x16x32_bf16 v[72:75], v[154:157], v[202:205], v[72:75]
	s_setprio 0
	s_setprio 1
	v_mfma_f32_16x16x32_bf16 v[116:119], v[158:161], v[174:177], v[116:119]
	v_mfma_f32_16x16x32_bf16 v[112:115], v[166:169], v[174:177], v[112:115]
	v_mfma_f32_16x16x32_bf16 v[100:103], v[158:161], v[182:185], v[100:103]
	v_mfma_f32_16x16x32_bf16 v[96:99], v[166:169], v[182:185], v[96:99]
	v_mfma_f32_16x16x32_bf16 v[84:87], v[158:161], v[190:193], v[84:87]
	v_mfma_f32_16x16x32_bf16 v[80:83], v[166:169], v[190:193], v[80:83]
	v_mfma_f32_16x16x32_bf16 v[68:71], v[158:161], v[198:201], v[68:71]
	v_mfma_f32_16x16x32_bf16 v[64:67], v[166:169], v[198:201], v[64:67]
	v_mfma_f32_16x16x32_bf16 v[116:119], v[162:165], v[178:181], v[116:119]
	v_mfma_f32_16x16x32_bf16 v[112:115], v[170:173], v[178:181], v[112:115]
	v_mfma_f32_16x16x32_bf16 v[100:103], v[162:165], v[186:189], v[100:103]
	v_mfma_f32_16x16x32_bf16 v[96:99], v[170:173], v[186:189], v[96:99]
	v_mfma_f32_16x16x32_bf16 v[84:87], v[162:165], v[194:197], v[84:87]
	v_mfma_f32_16x16x32_bf16 v[80:83], v[170:173], v[194:197], v[80:83]
	v_mfma_f32_16x16x32_bf16 v[68:71], v[162:165], v[202:205], v[68:71]
	v_mfma_f32_16x16x32_bf16 v[64:67], v[170:173], v[202:205], v[64:67]
	s_setprio 0
	s_waitcnt vmcnt(8)
	s_barrier
	s_add_i32 s65, s77, s3
	v_mov_b32_e32 v132, v129
	v_mov_b32_e32 v146, v131
	s_mov_b32 m0, s65
	ds_read_b128 v[174:177], v152 offset:16384
	ds_read_b128 v[178:181], v152 offset:17408
	ds_read_b128 v[182:185], v152 offset:18432
	ds_read_b128 v[186:189], v152 offset:19456
	ds_read_b128 v[190:193], v152 offset:20480
	ds_read_b128 v[194:197], v152 offset:21504
	ds_read_b128 v[198:201], v152 offset:22528
	ds_read_b128 v[202:205], v152 offset:23552
	s_nop 0
	global_load_lds_dwordx4 v132, s[46:47]
	s_add_i32 m0, s65, 0x2000
	s_add_u32 vcc_lo, s46, 0x70000
	s_addc_u32 vcc_hi, s47, 0
	s_add_i32 s65, s78, s3
	global_load_lds_dwordx4 v146, s[46:47]
	v_mov_b32_e32 v132, v129
	v_mov_b32_e32 v146, v131
	s_mov_b32 m0, s65
	s_nop 0
	global_load_lds_dwordx4 v132, vcc
	s_add_i32 m0, s65, 0x2000
	v_mov_b32_e32 v132, v128
	global_load_lds_dwordx4 v146, vcc
	v_mov_b32_e32 v146, v130
	s_mov_b32 m0, s37
	s_nop 0
	global_load_lds_dwordx4 v132, s[44:45]
	s_mov_b32 m0, s53
	s_nop 0
	global_load_lds_dwordx4 v146, s[44:45]
	s_and_b64 vcc, exec, s[16:17]
	s_cbranch_vccnz .Lmy_lw_6
	s_waitcnt vmcnt(8)
.Lmy_lw_6:
	s_waitcnt lgkmcnt(0)
	s_barrier
	s_setprio 1
	s_waitcnt lgkmcnt(0)
	v_mfma_f32_16x16x32_bf16 v[60:63], v[134:137], v[174:177], v[60:63]
	v_mfma_f32_16x16x32_bf16 v[56:59], v[142:145], v[174:177], v[56:59]
	v_mfma_f32_16x16x32_bf16 v[44:47], v[134:137], v[182:185], v[44:47]
	v_mfma_f32_16x16x32_bf16 v[40:43], v[142:145], v[182:185], v[40:43]
	v_mfma_f32_16x16x32_bf16 v[28:31], v[134:137], v[190:193], v[28:31]
	v_mfma_f32_16x16x32_bf16 v[24:27], v[142:145], v[190:193], v[24:27]
	v_mfma_f32_16x16x32_bf16 v[12:15], v[134:137], v[198:201], v[12:15]
	v_mfma_f32_16x16x32_bf16 v[8:11], v[142:145], v[198:201], v[8:11]
	v_mfma_f32_16x16x32_bf16 v[60:63], v[138:141], v[178:181], v[60:63]
	v_mfma_f32_16x16x32_bf16 v[56:59], v[154:157], v[178:181], v[56:59]
	v_mfma_f32_16x16x32_bf16 v[44:47], v[138:141], v[186:189], v[44:47]
	v_mfma_f32_16x16x32_bf16 v[40:43], v[154:157], v[186:189], v[40:43]
	v_mfma_f32_16x16x32_bf16 v[28:31], v[138:141], v[194:197], v[28:31]
	v_mfma_f32_16x16x32_bf16 v[24:27], v[154:157], v[194:197], v[24:27]
	v_mfma_f32_16x16x32_bf16 v[12:15], v[138:141], v[202:205], v[12:15]
	v_mfma_f32_16x16x32_bf16 v[8:11], v[154:157], v[202:205], v[8:11]
	s_setprio 0
	s_setprio 1
	v_mfma_f32_16x16x32_bf16 v[52:55], v[158:161], v[174:177], v[52:55]
	v_mfma_f32_16x16x32_bf16 v[48:51], v[166:169], v[174:177], v[48:51]
	v_mfma_f32_16x16x32_bf16 v[36:39], v[158:161], v[182:185], v[36:39]
	v_mfma_f32_16x16x32_bf16 v[32:35], v[166:169], v[182:185], v[32:35]
	v_mfma_f32_16x16x32_bf16 v[20:23], v[158:161], v[190:193], v[20:23]
	v_mfma_f32_16x16x32_bf16 v[16:19], v[166:169], v[190:193], v[16:19]
	v_mfma_f32_16x16x32_bf16 v[4:7], v[158:161], v[198:201], v[4:7]
	v_mfma_f32_16x16x32_bf16 v[0:3], v[166:169], v[198:201], v[0:3]
	v_mfma_f32_16x16x32_bf16 v[52:55], v[162:165], v[178:181], v[52:55]
	v_mfma_f32_16x16x32_bf16 v[48:51], v[170:173], v[178:181], v[48:51]
	v_mfma_f32_16x16x32_bf16 v[36:39], v[162:165], v[186:189], v[36:39]
	v_mfma_f32_16x16x32_bf16 v[32:35], v[170:173], v[186:189], v[32:35]
	v_mfma_f32_16x16x32_bf16 v[20:23], v[162:165], v[194:197], v[20:23]
	v_mfma_f32_16x16x32_bf16 v[16:19], v[170:173], v[194:197], v[16:19]
	v_mfma_f32_16x16x32_bf16 v[4:7], v[162:165], v[202:205], v[4:7]
	v_mfma_f32_16x16x32_bf16 v[0:3], v[170:173], v[202:205], v[0:3]
	s_setprio 0
	s_waitcnt vmcnt(8)
	s_barrier
	s_add_i32 s65, 0, 0x18000
	v_add_u32_e32 v132, s65, v149
	s_add_i32 s75, 0, 0x1c000
	ds_read_b128 v[134:137], v132
	ds_read_b128 v[138:141], v132 offset:1024
	ds_read_b128 v[142:145], v132 offset:2048
	ds_read_b128 v[154:157], v132 offset:3072
	v_add_u32_e32 v132, s75, v149
	ds_read_b128 v[158:161], v132
	ds_read_b128 v[162:165], v132 offset:1024
	ds_read_b128 v[166:169], v132 offset:2048
	ds_read_b128 v[170:173], v132 offset:3072
	s_add_u32 vcc_lo, s44, 0x70000
	v_mov_b32_e32 v132, v128
	v_mov_b32_e32 v146, v130
	s_addc_u32 vcc_hi, s45, 0
	s_mov_b32 m0, s54
	ds_read_b128 v[174:177], v152 offset:32768
	ds_read_b128 v[178:181], v152 offset:33792
	ds_read_b128 v[182:185], v152 offset:34816
	ds_read_b128 v[186:189], v152 offset:35840
	ds_read_b128 v[190:193], v152 offset:36864
	ds_read_b128 v[194:197], v152 offset:37888
	ds_read_b128 v[198:201], v152 offset:38912
	ds_read_b128 v[202:205], v152 offset:39936
	s_nop 0
	global_load_lds_dwordx4 v132, vcc
	s_mov_b32 m0, s55
	s_nop 0
	global_load_lds_dwordx4 v146, vcc
	s_and_b64 vcc, exec, s[16:17]
	s_cbranch_vccnz .Lmy_lw_7
	s_waitcnt vmcnt(8)
.Lmy_lw_7:
	s_waitcnt lgkmcnt(0)
	s_barrier
	s_setprio 1
	s_waitcnt lgkmcnt(0)
	v_mfma_f32_16x16x32_bf16 v[124:127], v[134:137], v[174:177], v[124:127]
	v_mfma_f32_16x16x32_bf16 v[120:123], v[142:145], v[174:177], v[120:123]
	v_mfma_f32_16x16x32_bf16 v[108:111], v[134:137], v[182:185], v[108:111]
	v_mfma_f32_16x16x32_bf16 v[104:107], v[142:145], v[182:185], v[104:107]
	v_mfma_f32_16x16x32_bf16 v[92:95], v[134:137], v[190:193], v[92:95]
	v_mfma_f32_16x16x32_bf16 v[88:91], v[142:145], v[190:193], v[88:91]
	v_mfma_f32_16x16x32_bf16 v[76:79], v[134:137], v[198:201], v[76:79]
	v_mfma_f32_16x16x32_bf16 v[72:75], v[142:145], v[198:201], v[72:75]
	v_mfma_f32_16x16x32_bf16 v[124:127], v[138:141], v[178:181], v[124:127]
	v_mfma_f32_16x16x32_bf16 v[120:123], v[154:157], v[178:181], v[120:123]
	v_mfma_f32_16x16x32_bf16 v[108:111], v[138:141], v[186:189], v[108:111]
	v_mfma_f32_16x16x32_bf16 v[104:107], v[154:157], v[186:189], v[104:107]
	v_mfma_f32_16x16x32_bf16 v[92:95], v[138:141], v[194:197], v[92:95]
	v_mfma_f32_16x16x32_bf16 v[88:91], v[154:157], v[194:197], v[88:91]
	v_mfma_f32_16x16x32_bf16 v[76:79], v[138:141], v[202:205], v[76:79]
	v_mfma_f32_16x16x32_bf16 v[72:75], v[154:157], v[202:205], v[72:75]
	s_setprio 0
	s_setprio 1
	v_mfma_f32_16x16x32_bf16 v[116:119], v[158:161], v[174:177], v[116:119]
	v_mfma_f32_16x16x32_bf16 v[112:115], v[166:169], v[174:177], v[112:115]
	v_mfma_f32_16x16x32_bf16 v[100:103], v[158:161], v[182:185], v[100:103]
	v_mfma_f32_16x16x32_bf16 v[96:99], v[166:169], v[182:185], v[96:99]
	v_mfma_f32_16x16x32_bf16 v[84:87], v[158:161], v[190:193], v[84:87]
	v_mfma_f32_16x16x32_bf16 v[80:83], v[166:169], v[190:193], v[80:83]
	v_mfma_f32_16x16x32_bf16 v[68:71], v[158:161], v[198:201], v[68:71]
	v_mfma_f32_16x16x32_bf16 v[64:67], v[166:169], v[198:201], v[64:67]
	v_mfma_f32_16x16x32_bf16 v[116:119], v[162:165], v[178:181], v[116:119]
	v_mfma_f32_16x16x32_bf16 v[112:115], v[170:173], v[178:181], v[112:115]
	v_mfma_f32_16x16x32_bf16 v[100:103], v[162:165], v[186:189], v[100:103]
	v_mfma_f32_16x16x32_bf16 v[96:99], v[170:173], v[186:189], v[96:99]
	v_mfma_f32_16x16x32_bf16 v[84:87], v[162:165], v[194:197], v[84:87]
	v_mfma_f32_16x16x32_bf16 v[80:83], v[170:173], v[194:197], v[80:83]
	v_mfma_f32_16x16x32_bf16 v[68:71], v[162:165], v[202:205], v[68:71]
	v_mfma_f32_16x16x32_bf16 v[64:67], v[170:173], v[202:205], v[64:67]
	s_setprio 0
	s_waitcnt vmcnt(8)
	s_barrier
	v_mov_b32_e32 v132, v129
	v_mov_b32_e32 v146, v131
	ds_read_b128 v[174:177], v152 offset:49152
	ds_read_b128 v[178:181], v152 offset:50176
	ds_read_b128 v[182:185], v152 offset:51200
	ds_read_b128 v[186:189], v152 offset:52224
	ds_read_b128 v[190:193], v152 offset:53248
	ds_read_b128 v[194:197], v152 offset:54272
	ds_read_b128 v[198:201], v152 offset:55296
	ds_read_b128 v[202:205], v152 offset:56320
	s_add_i32 s65, s65, s3
	v_lshl_add_u64 v[206:207], s[46:47], 0, v[132:133]
	v_lshl_add_u64 v[206:207], v[206:207], 0, s[14:15]
	s_mov_b32 m0, s65
	v_mov_b32_e32 v147, v133
	global_load_lds_dwordx4 v[206:207], off
	s_add_i32 m0, s65, 0x2000
	v_lshl_add_u64 v[146:147], s[46:47], 0, v[146:147]
	s_add_u32 s46, s46, 0x70080
	v_lshl_add_u64 v[146:147], v[146:147], 0, s[14:15]
	s_addc_u32 s47, s47, 0
	s_add_i32 s65, s75, s3
	global_load_lds_dwordx4 v[146:147], off
	v_mov_b32_e32 v132, v129
	v_mov_b32_e32 v146, v131
	s_mov_b32 m0, s65
	v_mov_b32_e32 v147, v133
	global_load_lds_dwordx4 v132, s[46:47]
	s_add_i32 m0, s65, 0x2000
	v_mov_b32_e32 v132, v128
	global_load_lds_dwordx4 v146, s[46:47]
	v_mov_b32_e32 v146, v130
	s_mov_b32 m0, s68
	v_lshl_add_u64 v[206:207], s[44:45], 0, v[132:133]
	v_lshl_add_u64 v[206:207], v[206:207], 0, s[14:15]
	v_lshl_add_u64 v[146:147], s[44:45], 0, v[146:147]
	global_load_lds_dwordx4 v[206:207], off
	v_lshl_add_u64 v[146:147], v[146:147], 0, s[14:15]
	s_mov_b32 m0, s69
	s_nop 0
	global_load_lds_dwordx4 v[146:147], off
	s_and_b64 vcc, exec, s[16:17]
	s_cbranch_vccnz .Lmy_lw_8
	s_waitcnt vmcnt(8)
.Lmy_lw_8:
	s_waitcnt lgkmcnt(0)
	s_barrier
	s_setprio 1
	s_waitcnt lgkmcnt(0)
	v_mfma_f32_16x16x32_bf16 v[60:63], v[134:137], v[174:177], v[60:63]
	v_mfma_f32_16x16x32_bf16 v[56:59], v[142:145], v[174:177], v[56:59]
	v_mfma_f32_16x16x32_bf16 v[44:47], v[134:137], v[182:185], v[44:47]
	v_mfma_f32_16x16x32_bf16 v[40:43], v[142:145], v[182:185], v[40:43]
	v_mfma_f32_16x16x32_bf16 v[28:31], v[134:137], v[190:193], v[28:31]
	v_mfma_f32_16x16x32_bf16 v[24:27], v[142:145], v[190:193], v[24:27]
	v_mfma_f32_16x16x32_bf16 v[12:15], v[134:137], v[198:201], v[12:15]
	v_mfma_f32_16x16x32_bf16 v[8:11], v[142:145], v[198:201], v[8:11]
	v_mfma_f32_16x16x32_bf16 v[60:63], v[138:141], v[178:181], v[60:63]
	v_mfma_f32_16x16x32_bf16 v[56:59], v[154:157], v[178:181], v[56:59]
	v_mfma_f32_16x16x32_bf16 v[44:47], v[138:141], v[186:189], v[44:47]
	v_mfma_f32_16x16x32_bf16 v[40:43], v[154:157], v[186:189], v[40:43]
	v_mfma_f32_16x16x32_bf16 v[28:31], v[138:141], v[194:197], v[28:31]
	v_mfma_f32_16x16x32_bf16 v[24:27], v[154:157], v[194:197], v[24:27]
	v_mfma_f32_16x16x32_bf16 v[12:15], v[138:141], v[202:205], v[12:15]
	v_mfma_f32_16x16x32_bf16 v[8:11], v[154:157], v[202:205], v[8:11]
	s_setprio 0
	s_setprio 1
	v_mfma_f32_16x16x32_bf16 v[52:55], v[158:161], v[174:177], v[52:55]
	v_mfma_f32_16x16x32_bf16 v[48:51], v[166:169], v[174:177], v[48:51]
	v_mfma_f32_16x16x32_bf16 v[36:39], v[158:161], v[182:185], v[36:39]
	v_mfma_f32_16x16x32_bf16 v[32:35], v[166:169], v[182:185], v[32:35]
	v_mfma_f32_16x16x32_bf16 v[20:23], v[158:161], v[190:193], v[20:23]
	v_mfma_f32_16x16x32_bf16 v[16:19], v[166:169], v[190:193], v[16:19]
	v_mfma_f32_16x16x32_bf16 v[4:7], v[158:161], v[198:201], v[4:7]
	v_mfma_f32_16x16x32_bf16 v[0:3], v[166:169], v[198:201], v[0:3]
	v_mfma_f32_16x16x32_bf16 v[52:55], v[162:165], v[178:181], v[52:55]
	v_mfma_f32_16x16x32_bf16 v[48:51], v[170:173], v[178:181], v[48:51]
	v_mfma_f32_16x16x32_bf16 v[36:39], v[162:165], v[186:189], v[36:39]
	v_mfma_f32_16x16x32_bf16 v[32:35], v[170:173], v[186:189], v[32:35]
	v_mfma_f32_16x16x32_bf16 v[20:23], v[162:165], v[194:197], v[20:23]
	v_mfma_f32_16x16x32_bf16 v[16:19], v[170:173], v[194:197], v[16:19]
	v_mfma_f32_16x16x32_bf16 v[4:7], v[162:165], v[202:205], v[4:7]
	v_mfma_f32_16x16x32_bf16 v[0:3], v[170:173], v[202:205], v[0:3]
	s_setprio 0
	s_waitcnt vmcnt(8)
	s_barrier
	s_add_u32 s6, s6, 0x100
	s_addc_u32 s7, s7, 0
	s_add_u32 s96, s96, 0x100
	s_addc_u32 s97, s97, 0
	s_cmp_ge_i32 s64, s51
	s_mov_b32 s44, s64
	s_cbranch_scc0 .LBB0_780
	s_and_b64 vcc, exec, s[16:17]
	s_cbranch_vccz .LBB0_783
	s_barrier

.LBB0_1273:
	ds_read_b128 v[130:133], v146
	ds_read_b128 v[134:137], v146 offset:1024
	ds_read_b128 v[150:153], v146 offset:2048
	ds_read_b128 v[154:157], v146 offset:3072
	ds_read_b128 v[158:161], v147
	ds_read_b128 v[162:165], v147 offset:1024
	ds_read_b128 v[166:169], v147 offset:2048
	ds_read_b128 v[170:173], v147 offset:3072
	s_add_u32 s44, s42, 0xfffc0080
	s_addc_u32 s45, s43, -1
	s_cmp_eq_u32 s49, 12
	s_cselect_b32 s45, s35, s45
	s_cselect_b32 s44, s34, s44
	s_cselect_b32 s47, s37, s48
	s_cselect_b32 s46, s36, s31
	v_mov_b32_e32 v128, v142
	v_mov_b32_e32 v138, v141
	s_add_i32 m0, s53, 0xc000
	ds_read_b128 v[174:177], v148
	ds_read_b128 v[178:181], v148 offset:1024
	ds_read_b128 v[182:185], v148 offset:2048
	ds_read_b128 v[186:189], v148 offset:3072
	ds_read_b128 v[190:193], v148 offset:4096
	ds_read_b128 v[194:197], v148 offset:5120
	ds_read_b128 v[198:201], v148 offset:6144
	ds_read_b128 v[202:205], v148 offset:7168
	s_nop 0
	global_load_lds_dwordx4 v138, s[42:43]
	s_add_i32 m0, s53, 0xe000
	s_nop 0
	global_load_lds_dwordx4 v128, s[42:43]
	s_and_b64 vcc, exec, s[20:21]
	s_cbranch_vccnz .Lmy_lw_9
	s_waitcnt vmcnt(8)
.Lmy_lw_9:
	s_waitcnt lgkmcnt(0)
	s_barrier
	s_setprio 1
	s_waitcnt lgkmcnt(0)
	v_mfma_scale_f32_16x16x128_f8f6f4 v[124:127], v[130:137], v[174:181], v[124:127], v149, v149 op_sel_hi:[0,0,0]
	v_mfma_scale_f32_16x16x128_f8f6f4 v[120:123], v[150:157], v[174:181], v[120:123], v149, v149 op_sel_hi:[0,0,0]
	v_mfma_scale_f32_16x16x128_f8f6f4 v[108:111], v[130:137], v[182:189], v[108:111], v149, v149 op_sel_hi:[0,0,0]
	v_mfma_scale_f32_16x16x128_f8f6f4 v[104:107], v[150:157], v[182:189], v[104:107], v149, v149 op_sel_hi:[0,0,0]
	v_mfma_scale_f32_16x16x128_f8f6f4 v[206:209], v[130:137], v[190:197], v[92:95], v149, v149 op_sel_hi:[0,0,0]
	v_mfma_scale_f32_16x16x128_f8f6f4 v[214:217], v[150:157], v[190:197], v[88:91], v149, v149 op_sel_hi:[0,0,0]
	v_mfma_scale_f32_16x16x128_f8f6f4 v[218:221], v[130:137], v[198:205], v[76:79], v149, v149 op_sel_hi:[0,0,0]
	v_mfma_scale_f32_16x16x128_f8f6f4 v[222:225], v[150:157], v[198:205], v[72:75], v149, v149 op_sel_hi:[0,0,0]
	s_setprio 0
	s_setprio 1
	v_mfma_scale_f32_16x16x128_f8f6f4 v[116:119], v[158:165], v[174:181], v[116:119], v149, v149 op_sel_hi:[0,0,0]
	v_mfma_scale_f32_16x16x128_f8f6f4 v[112:115], v[166:173], v[174:181], v[112:115], v149, v149 op_sel_hi:[0,0,0]
	v_mfma_scale_f32_16x16x128_f8f6f4 v[100:103], v[158:165], v[182:189], v[100:103], v149, v149 op_sel_hi:[0,0,0]
	v_mfma_scale_f32_16x16x128_f8f6f4 v[96:99], v[166:173], v[182:189], v[96:99], v149, v149 op_sel_hi:[0,0,0]
	v_mfma_scale_f32_16x16x128_f8f6f4 v[174:177], v[158:165], v[190:197], v[84:87], v149, v149 op_sel_hi:[0,0,0]
	v_mfma_scale_f32_16x16x128_f8f6f4 v[178:181], v[166:173], v[190:197], v[80:83], v149, v149 op_sel_hi:[0,0,0]
	v_mfma_scale_f32_16x16x128_f8f6f4 v[182:185], v[158:165], v[198:205], v[68:71], v149, v149 op_sel_hi:[0,0,0]
	v_mfma_scale_f32_16x16x128_f8f6f4 v[186:189], v[166:173], v[198:205], v[64:67], v149, v149 op_sel_hi:[0,0,0]
	s_setprio 0
	s_waitcnt vmcnt(8)
	s_barrier
	s_add_i32 s64, s71, s3
	v_mov_b32_e32 v128, v144
	v_mov_b32_e32 v138, v143
	s_mov_b32 m0, s64
	s_nop 0
	ds_read_b128 v[64:67], v148 offset:16384
	ds_read_b128 v[68:71], v148 offset:17408
	ds_read_b128 v[72:75], v148 offset:18432
	ds_read_b128 v[76:79], v148 offset:19456
	ds_read_b128 v[80:83], v148 offset:20480
	ds_read_b128 v[84:87], v148 offset:21504
	ds_read_b128 v[88:91], v148 offset:22528
	ds_read_b128 v[92:95], v148 offset:23552
	v_mov_b32_e32 v139, v129
	global_load_lds_dwordx4 v138, s[46:47]
	s_add_i32 m0, s64, 0x2000
	v_mov_b32_e32 v138, v144
	global_load_lds_dwordx4 v128, s[46:47]
	v_mov_b32_e32 v128, v143
	s_add_i32 s64, s72, s3
	v_lshl_add_u64 v[190:191], s[46:47], 0, v[128:129]
	v_lshl_add_u64 v[190:191], v[190:191], 0, s[14:15]
	s_mov_b32 m0, s64
	v_lshl_add_u64 v[138:139], s[46:47], 0, v[138:139]
	global_load_lds_dwordx4 v[190:191], off
	v_lshl_add_u64 v[138:139], v[138:139], 0, s[14:15]
	s_add_i32 m0, s64, 0x2000
	v_mov_b32_e32 v128, v142
	global_load_lds_dwordx4 v[138:139], off
	v_mov_b32_e32 v138, v141
	s_mov_b32 m0, s53
	s_nop 0
	global_load_lds_dwordx4 v138, s[44:45]
	s_mov_b32 m0, s54
	s_nop 0
	global_load_lds_dwordx4 v128, s[44:45]
	s_and_b64 vcc, exec, s[20:21]
	s_cbranch_vccnz .Lmy_lw_10
	s_waitcnt vmcnt(8)
.Lmy_lw_10:
	s_waitcnt lgkmcnt(0)
	s_barrier
	s_setprio 1
	s_waitcnt lgkmcnt(0)
	v_mfma_scale_f32_16x16x128_f8f6f4 v[60:63], v[130:137], v[64:71], v[60:63], v149, v149 op_sel_hi:[0,0,0]
	v_mfma_scale_f32_16x16x128_f8f6f4 v[56:59], v[150:157], v[64:71], v[56:59], v149, v149 op_sel_hi:[0,0,0]
	v_mfma_scale_f32_16x16x128_f8f6f4 v[190:193], v[130:137], v[72:79], v[44:47], v149, v149 op_sel_hi:[0,0,0]
	v_mfma_scale_f32_16x16x128_f8f6f4 v[194:197], v[150:157], v[72:79], v[40:43], v149, v149 op_sel_hi:[0,0,0]
	v_mfma_scale_f32_16x16x128_f8f6f4 v[198:201], v[130:137], v[80:87], v[28:31], v149, v149 op_sel_hi:[0,0,0]
	v_mfma_scale_f32_16x16x128_f8f6f4 v[202:205], v[150:157], v[80:87], v[24:27], v149, v149 op_sel_hi:[0,0,0]
	v_mfma_scale_f32_16x16x128_f8f6f4 v[226:229], v[130:137], v[88:95], v[12:15], v149, v149 op_sel_hi:[0,0,0]
	v_mfma_scale_f32_16x16x128_f8f6f4 v[230:233], v[150:157], v[88:95], v[8:11], v149, v149 op_sel_hi:[0,0,0]
	s_setprio 0
	s_setprio 1
	v_mfma_scale_f32_16x16x128_f8f6f4 v[52:55], v[158:165], v[64:71], v[52:55], v149, v149 op_sel_hi:[0,0,0]
	v_mfma_scale_f32_16x16x128_f8f6f4 v[48:51], v[166:173], v[64:71], v[48:51], v149, v149 op_sel_hi:[0,0,0]
	v_mfma_scale_f32_16x16x128_f8f6f4 v[234:237], v[158:165], v[72:79], v[36:39], v149, v149 op_sel_hi:[0,0,0]
	v_mfma_scale_f32_16x16x128_f8f6f4 v[238:241], v[166:173], v[72:79], v[32:35], v149, v149 op_sel_hi:[0,0,0]
	v_mfma_scale_f32_16x16x128_f8f6f4 v[242:245], v[158:165], v[80:87], v[20:23], v149, v149 op_sel_hi:[0,0,0]
	v_mfma_scale_f32_16x16x128_f8f6f4 v[246:249], v[166:173], v[80:87], v[16:19], v149, v149 op_sel_hi:[0,0,0]
	v_mfma_scale_f32_16x16x128_f8f6f4 v[250:253], v[158:165], v[88:95], v[4:7], v149, v149 op_sel_hi:[0,0,0]
	v_mfma_scale_f32_16x16x128_f8f6f4 v[210:213], v[166:173], v[88:95], v[0:3], v149, v149 op_sel_hi:[0,0,0]
	s_setprio 0
	s_waitcnt vmcnt(8)
	s_barrier
	s_add_i32 s77, 0, 0x18000
	v_add_u32_e32 v8, s77, v145
	s_add_i32 s78, 0, 0x1c000
	s_nop 1
	ds_read_b128 v[0:3], v8
	ds_read_b128 v[4:7], v8 offset:1024
	ds_read_b128 v[16:19], v8 offset:2048
	ds_read_b128 v[20:23], v8 offset:3072
	v_add_u32_e32 v8, s78, v145
	ds_read_b128 v[130:133], v8
	ds_read_b128 v[134:137], v8 offset:1024
	ds_read_b128 v[150:153], v8 offset:2048
	ds_read_b128 v[154:157], v8 offset:3072
	s_add_u32 s64, s44, 0x40000
	v_mov_b32_e32 v64, v142
	v_mov_b32_e32 v65, v141
	s_addc_u32 s65, s45, 0
	s_mov_b32 m0, s55
	ds_read_b128 v[8:11], v148 offset:32768
	ds_read_b128 v[12:15], v148 offset:33792
	ds_read_b128 v[24:27], v148 offset:34816
	ds_read_b128 v[28:31], v148 offset:35840
	ds_read_b128 v[32:35], v148 offset:36864
	ds_read_b128 v[36:39], v148 offset:37888
	ds_read_b128 v[40:43], v148 offset:38912
	ds_read_b128 v[44:47], v148 offset:39936
	s_nop 0
	global_load_lds_dwordx4 v65, s[64:65]
	s_mov_b32 m0, s63
	s_nop 0
	global_load_lds_dwordx4 v64, s[64:65]
	s_and_b64 vcc, exec, s[20:21]
	s_cbranch_vccnz .Lmy_lw_11
	s_waitcnt vmcnt(8)
.Lmy_lw_11:
	s_waitcnt lgkmcnt(0)
	s_barrier
	s_setprio 1
	s_waitcnt lgkmcnt(0)
	v_mfma_scale_f32_16x16x128_f8f6f4 v[124:127], v[0:7], v[8:15], v[124:127], v149, v149 op_sel_hi:[0,0,0]
	v_mfma_scale_f32_16x16x128_f8f6f4 v[120:123], v[16:23], v[8:15], v[120:123], v149, v149 op_sel_hi:[0,0,0]
	v_mfma_scale_f32_16x16x128_f8f6f4 v[108:111], v[0:7], v[24:31], v[108:111], v149, v149 op_sel_hi:[0,0,0]
	v_mfma_scale_f32_16x16x128_f8f6f4 v[104:107], v[16:23], v[24:31], v[104:107], v149, v149 op_sel_hi:[0,0,0]
	v_mfma_scale_f32_16x16x128_f8f6f4 v[92:95], v[0:7], v[32:39], v[206:209], v149, v149 op_sel_hi:[0,0,0]
	v_mfma_scale_f32_16x16x128_f8f6f4 v[88:91], v[16:23], v[32:39], v[214:217], v149, v149 op_sel_hi:[0,0,0]
	v_mfma_scale_f32_16x16x128_f8f6f4 v[76:79], v[0:7], v[40:47], v[218:221], v149, v149 op_sel_hi:[0,0,0]
	v_mfma_scale_f32_16x16x128_f8f6f4 v[72:75], v[16:23], v[40:47], v[222:225], v149, v149 op_sel_hi:[0,0,0]
	s_setprio 0
	s_setprio 1
	v_mfma_scale_f32_16x16x128_f8f6f4 v[116:119], v[130:137], v[8:15], v[116:119], v149, v149 op_sel_hi:[0,0,0]
	v_mfma_scale_f32_16x16x128_f8f6f4 v[112:115], v[150:157], v[8:15], v[112:115], v149, v149 op_sel_hi:[0,0,0]
	v_mfma_scale_f32_16x16x128_f8f6f4 v[100:103], v[130:137], v[24:31], v[100:103], v149, v149 op_sel_hi:[0,0,0]
	v_mfma_scale_f32_16x16x128_f8f6f4 v[96:99], v[150:157], v[24:31], v[96:99], v149, v149 op_sel_hi:[0,0,0]
	v_mfma_scale_f32_16x16x128_f8f6f4 v[84:87], v[130:137], v[32:39], v[174:177], v149, v149 op_sel_hi:[0,0,0]
	v_mfma_scale_f32_16x16x128_f8f6f4 v[80:83], v[150:157], v[32:39], v[178:181], v149, v149 op_sel_hi:[0,0,0]
	v_mfma_scale_f32_16x16x128_f8f6f4 v[68:71], v[130:137], v[40:47], v[182:185], v149, v149 op_sel_hi:[0,0,0]
	v_mfma_scale_f32_16x16x128_f8f6f4 v[64:67], v[150:157], v[40:47], v[186:189], v149, v149 op_sel_hi:[0,0,0]
	s_setprio 0
	s_waitcnt vmcnt(8)
	s_barrier
	s_add_u32 s64, s46, 0x40000
	s_addc_u32 s65, s47, 0
	s_add_i32 s77, s77, s3
	v_mov_b32_e32 v8, v144
	v_mov_b32_e32 v9, v143
	s_mov_b32 m0, s77
	ds_read_b128 v[32:35], v148 offset:49152
	ds_read_b128 v[36:39], v148 offset:50176
	ds_read_b128 v[158:161], v148 offset:51200
	ds_read_b128 v[162:165], v148 offset:52224
	ds_read_b128 v[166:169], v148 offset:53248
	ds_read_b128 v[170:173], v148 offset:54272
	ds_read_b128 v[174:177], v148 offset:55296
	ds_read_b128 v[178:181], v148 offset:56320
	v_mov_b32_e32 v128, v141
	global_load_lds_dwordx4 v9, s[64:65]
	s_add_i32 m0, s77, 0x2000
	s_add_u32 s46, s46, 0x40800
	global_load_lds_dwordx4 v8, s[64:65]
	s_addc_u32 s47, s47, 0
	s_add_i32 s64, s78, s3
	v_mov_b32_e32 v8, v144
	v_mov_b32_e32 v9, v143
	s_mov_b32 m0, s64
	s_nop 0
	global_load_lds_dwordx4 v9, s[46:47]
	s_add_i32 m0, s64, 0x2000
	v_mov_b32_e32 v9, v129
	global_load_lds_dwordx4 v8, s[46:47]
	v_mov_b32_e32 v8, v142
	s_mov_b32 m0, s68
	v_lshl_add_u64 v[10:11], s[44:45], 0, v[128:129]
	v_lshl_add_u64 v[10:11], v[10:11], 0, s[18:19]
	v_lshl_add_u64 v[8:9], s[44:45], 0, v[8:9]
	global_load_lds_dwordx4 v[10:11], off
	v_lshl_add_u64 v[8:9], v[8:9], 0, s[18:19]
	s_mov_b32 m0, s69
	s_nop 0
	global_load_lds_dwordx4 v[8:9], off
	s_and_b64 vcc, exec, s[20:21]
	s_cbranch_vccnz .Lmy_lw_12
	s_waitcnt vmcnt(8)
.Lmy_lw_12:
	s_waitcnt lgkmcnt(0)
	s_barrier
	s_setprio 1
	s_waitcnt lgkmcnt(0)
	v_mfma_scale_f32_16x16x128_f8f6f4 v[60:63], v[0:7], v[32:39], v[60:63], v149, v149 op_sel_hi:[0,0,0]
	v_mfma_scale_f32_16x16x128_f8f6f4 v[56:59], v[16:23], v[32:39], v[56:59], v149, v149 op_sel_hi:[0,0,0]
	v_mfma_scale_f32_16x16x128_f8f6f4 v[44:47], v[0:7], v[158:165], v[190:193], v149, v149 op_sel_hi:[0,0,0]
	v_mfma_scale_f32_16x16x128_f8f6f4 v[40:43], v[16:23], v[158:165], v[194:197], v149, v149 op_sel_hi:[0,0,0]
	v_mfma_scale_f32_16x16x128_f8f6f4 v[28:31], v[0:7], v[166:173], v[198:201], v149, v149 op_sel_hi:[0,0,0]
	v_mfma_scale_f32_16x16x128_f8f6f4 v[24:27], v[16:23], v[166:173], v[202:205], v149, v149 op_sel_hi:[0,0,0]
	v_mfma_scale_f32_16x16x128_f8f6f4 v[12:15], v[0:7], v[174:181], v[226:229], v149, v149 op_sel_hi:[0,0,0]
	v_mfma_scale_f32_16x16x128_f8f6f4 v[8:11], v[16:23], v[174:181], v[230:233], v149, v149 op_sel_hi:[0,0,0]
	s_setprio 0
	s_setprio 1
	v_mfma_scale_f32_16x16x128_f8f6f4 v[52:55], v[130:137], v[32:39], v[52:55], v149, v149 op_sel_hi:[0,0,0]
	v_mfma_scale_f32_16x16x128_f8f6f4 v[48:51], v[150:157], v[32:39], v[48:51], v149, v149 op_sel_hi:[0,0,0]
	v_mfma_scale_f32_16x16x128_f8f6f4 v[36:39], v[130:137], v[158:165], v[234:237], v149, v149 op_sel_hi:[0,0,0]
	v_mfma_scale_f32_16x16x128_f8f6f4 v[32:35], v[150:157], v[158:165], v[238:241], v149, v149 op_sel_hi:[0,0,0]
	v_mfma_scale_f32_16x16x128_f8f6f4 v[20:23], v[130:137], v[166:173], v[242:245], v149, v149 op_sel_hi:[0,0,0]
	v_mfma_scale_f32_16x16x128_f8f6f4 v[16:19], v[150:157], v[166:173], v[246:249], v149, v149 op_sel_hi:[0,0,0]
	v_mfma_scale_f32_16x16x128_f8f6f4 v[4:7], v[130:137], v[174:181], v[250:253], v149, v149 op_sel_hi:[0,0,0]
	v_mfma_scale_f32_16x16x128_f8f6f4 v[0:3], v[150:157], v[174:181], v[210:213], v149, v149 op_sel_hi:[0,0,0]
	s_setprio 0
	s_waitcnt vmcnt(8)
	s_barrier
	s_add_i32 s49, s49, 2
	s_add_u32 s31, s31, 0x80000
	s_addc_u32 s48, s48, 0
	s_add_u32 s42, s42, 0x100
	s_addc_u32 s43, s43, 0
	s_cmp_gt_u32 s49, 13
	s_cbranch_scc0 .LBB0_1273
	s_and_b64 vcc, exec, s[20:21]
	s_cbranch_vccz .LBB0_1276
	s_barrier

.LBB0_1751:
	ds_read_b128 v[144:147], v140
	ds_read_b128 v[148:151], v140 offset:1024
	ds_read_b128 v[152:155], v140 offset:2048
	ds_read_b128 v[156:159], v140 offset:3072
	ds_read_b128 v[160:163], v141
	ds_read_b128 v[164:167], v141 offset:1024
	ds_read_b128 v[168:171], v141 offset:2048
	ds_read_b128 v[172:175], v141 offset:3072
	s_add_u32 s30, s28, 0xfffc0080
	s_addc_u32 s31, s29, -1
	s_cmp_eq_u32 s49, 12
	s_cselect_b32 s31, s21, s31
	s_cselect_b32 s30, s20, s30
	s_cselect_b32 s35, s23, s48
	s_cselect_b32 s34, s22, s19
	v_mov_b32_e32 v128, v136
	v_mov_b32_e32 v130, v135
	s_add_i32 m0, s40, 0xc000
	ds_read_b128 v[176:179], v142
	ds_read_b128 v[180:183], v142 offset:1024
	ds_read_b128 v[184:187], v142 offset:2048
	ds_read_b128 v[188:191], v142 offset:3072
	ds_read_b128 v[192:195], v142 offset:4096
	ds_read_b128 v[196:199], v142 offset:5120
	ds_read_b128 v[200:203], v142 offset:6144
	ds_read_b128 v[204:207], v142 offset:7168
	s_nop 0
	global_load_lds_dwordx4 v130, s[28:29]
	s_add_i32 m0, s40, 0xe000
	s_nop 0
	global_load_lds_dwordx4 v128, s[28:29]
	s_and_b64 vcc, exec, s[14:15]
	s_cbranch_vccnz .Lmy_lw_17
	s_waitcnt vmcnt(8)
.Lmy_lw_17:
	s_waitcnt lgkmcnt(0)
	s_barrier
	s_setprio 1
	s_waitcnt lgkmcnt(0)
	v_mfma_scale_f32_16x16x128_f8f6f4 v[124:127], v[144:151], v[176:183], v[124:127], v143, v143 op_sel_hi:[0,0,0]
	v_mfma_scale_f32_16x16x128_f8f6f4 v[120:123], v[152:159], v[176:183], v[120:123], v143, v143 op_sel_hi:[0,0,0]
	v_mfma_scale_f32_16x16x128_f8f6f4 v[112:115], v[144:151], v[184:191], v[112:115], v143, v143 op_sel_hi:[0,0,0]
	v_mfma_scale_f32_16x16x128_f8f6f4 v[104:107], v[152:159], v[184:191], v[104:107], v143, v143 op_sel_hi:[0,0,0]
	v_mfma_scale_f32_16x16x128_f8f6f4 v[96:99], v[144:151], v[192:199], v[96:99], v143, v143 op_sel_hi:[0,0,0]
	v_mfma_scale_f32_16x16x128_f8f6f4 v[130:133], v[152:159], v[192:199], v[88:91], v143, v143 op_sel_hi:[0,0,0]
	v_mfma_scale_f32_16x16x128_f8f6f4 v[208:211], v[144:151], v[200:207], v[80:83], v143, v143 op_sel_hi:[0,0,0]
	v_mfma_scale_f32_16x16x128_f8f6f4 v[212:215], v[152:159], v[200:207], v[72:75], v143, v143 op_sel_hi:[0,0,0]
	s_setprio 0
	s_setprio 1
	v_mfma_scale_f32_16x16x128_f8f6f4 v[116:119], v[160:167], v[176:183], v[116:119], v143, v143 op_sel_hi:[0,0,0]
	v_mfma_scale_f32_16x16x128_f8f6f4 v[108:111], v[168:175], v[176:183], v[108:111], v143, v143 op_sel_hi:[0,0,0]
	v_mfma_scale_f32_16x16x128_f8f6f4 v[100:103], v[160:167], v[184:191], v[100:103], v143, v143 op_sel_hi:[0,0,0]
	v_mfma_scale_f32_16x16x128_f8f6f4 v[176:179], v[168:175], v[184:191], v[92:95], v143, v143 op_sel_hi:[0,0,0]
	v_mfma_scale_f32_16x16x128_f8f6f4 v[180:183], v[160:167], v[192:199], v[84:87], v143, v143 op_sel_hi:[0,0,0]
	v_mfma_scale_f32_16x16x128_f8f6f4 v[184:187], v[168:175], v[192:199], v[76:79], v143, v143 op_sel_hi:[0,0,0]
	v_mfma_scale_f32_16x16x128_f8f6f4 v[188:191], v[160:167], v[200:207], v[68:71], v143, v143 op_sel_hi:[0,0,0]
	v_mfma_scale_f32_16x16x128_f8f6f4 v[192:195], v[168:175], v[200:207], v[64:67], v143, v143 op_sel_hi:[0,0,0]
	s_setprio 0
	s_waitcnt vmcnt(8)
	s_barrier
	s_add_i32 s63, s53, s3
	v_mov_b32_e32 v128, v138
	v_mov_b32_e32 v196, v137
	s_mov_b32 m0, s63
	s_nop 0
	ds_read_b128 v[64:67], v142 offset:16384
	ds_read_b128 v[68:71], v142 offset:17408
	ds_read_b128 v[72:75], v142 offset:18432
	ds_read_b128 v[76:79], v142 offset:19456
	ds_read_b128 v[80:83], v142 offset:20480
	ds_read_b128 v[84:87], v142 offset:21504
	ds_read_b128 v[88:91], v142 offset:22528
	ds_read_b128 v[92:95], v142 offset:23552
	v_mov_b32_e32 v197, v129
	global_load_lds_dwordx4 v196, s[34:35]
	s_add_i32 m0, s63, 0x2000
	v_mov_b32_e32 v196, v138
	global_load_lds_dwordx4 v128, s[34:35]
	v_mov_b32_e32 v128, v137
	s_add_i32 s63, s54, s3
	v_lshl_add_u64 v[198:199], s[34:35], 0, v[128:129]
	v_lshl_add_u64 v[198:199], v[198:199], 0, s[8:9]
	s_mov_b32 m0, s63
	v_lshl_add_u64 v[196:197], s[34:35], 0, v[196:197]
	global_load_lds_dwordx4 v[198:199], off
	v_lshl_add_u64 v[196:197], v[196:197], 0, s[8:9]
	s_add_i32 m0, s63, 0x2000
	v_mov_b32_e32 v128, v136
	global_load_lds_dwordx4 v[196:197], off
	v_mov_b32_e32 v196, v135
	s_mov_b32 m0, s40
	s_nop 0
	global_load_lds_dwordx4 v196, s[30:31]
	s_mov_b32 m0, s41
	s_nop 0
	global_load_lds_dwordx4 v128, s[30:31]
	s_and_b64 vcc, exec, s[14:15]
	s_cbranch_vccnz .Lmy_lw_18
	s_waitcnt vmcnt(8)
.Lmy_lw_18:
	s_waitcnt lgkmcnt(0)
	s_barrier
	s_setprio 1
	s_waitcnt lgkmcnt(0)
	v_mfma_scale_f32_16x16x128_f8f6f4 v[60:63], v[144:151], v[64:71], v[60:63], v143, v143 op_sel_hi:[0,0,0]
	v_mfma_scale_f32_16x16x128_f8f6f4 v[56:59], v[152:159], v[64:71], v[56:59], v143, v143 op_sel_hi:[0,0,0]
	v_mfma_scale_f32_16x16x128_f8f6f4 v[48:51], v[144:151], v[72:79], v[48:51], v143, v143 op_sel_hi:[0,0,0]
	v_mfma_scale_f32_16x16x128_f8f6f4 v[196:199], v[152:159], v[72:79], v[40:43], v143, v143 op_sel_hi:[0,0,0]
	v_mfma_scale_f32_16x16x128_f8f6f4 v[200:203], v[144:151], v[80:87], v[32:35], v143, v143 op_sel_hi:[0,0,0]
	v_mfma_scale_f32_16x16x128_f8f6f4 v[204:207], v[152:159], v[80:87], v[24:27], v143, v143 op_sel_hi:[0,0,0]
	v_mfma_scale_f32_16x16x128_f8f6f4 v[216:219], v[144:151], v[88:95], v[16:19], v143, v143 op_sel_hi:[0,0,0]
	v_mfma_scale_f32_16x16x128_f8f6f4 v[220:223], v[152:159], v[88:95], v[8:11], v143, v143 op_sel_hi:[0,0,0]
	s_setprio 0
	s_setprio 1
	v_mfma_scale_f32_16x16x128_f8f6f4 v[52:55], v[160:167], v[64:71], v[52:55], v143, v143 op_sel_hi:[0,0,0]
	v_mfma_scale_f32_16x16x128_f8f6f4 v[224:227], v[168:175], v[64:71], v[44:47], v143, v143 op_sel_hi:[0,0,0]
	v_mfma_scale_f32_16x16x128_f8f6f4 v[228:231], v[160:167], v[72:79], v[36:39], v143, v143 op_sel_hi:[0,0,0]
	v_mfma_scale_f32_16x16x128_f8f6f4 v[232:235], v[168:175], v[72:79], v[28:31], v143, v143 op_sel_hi:[0,0,0]
	v_mfma_scale_f32_16x16x128_f8f6f4 v[236:239], v[160:167], v[80:87], v[20:23], v143, v143 op_sel_hi:[0,0,0]
	v_mfma_scale_f32_16x16x128_f8f6f4 v[240:243], v[168:175], v[80:87], v[12:15], v143, v143 op_sel_hi:[0,0,0]
	v_mfma_scale_f32_16x16x128_f8f6f4 v[244:247], v[160:167], v[88:95], v[4:7], v143, v143 op_sel_hi:[0,0,0]
	v_mfma_scale_f32_16x16x128_f8f6f4 v[248:251], v[168:175], v[88:95], v[0:3], v143, v143 op_sel_hi:[0,0,0]
	s_setprio 0
	s_waitcnt vmcnt(8)
	s_barrier
	s_add_i32 s63, 0, 0x18000
	s_add_i32 s66, 0, 0x1c000
	s_nop 0
	v_add_u32_e32 v12, s63, v139
	v_add_u32_e32 v16, s66, v139
	ds_read_b128 v[0:3], v12
	ds_read_b128 v[4:7], v12 offset:1024
	ds_read_b128 v[8:11], v12 offset:2048
	ds_read_b128 v[12:15], v12 offset:3072
	ds_read_b128 v[144:147], v16
	ds_read_b128 v[148:151], v16 offset:1024
	ds_read_b128 v[152:155], v16 offset:2048
	ds_read_b128 v[156:159], v16 offset:3072
	s_add_u32 s64, s30, 0x40000
	v_mov_b32_e32 v64, v136
	v_mov_b32_e32 v65, v135
	s_addc_u32 s65, s31, 0
	s_mov_b32 m0, s42
	ds_read_b128 v[16:19], v142 offset:32768
	ds_read_b128 v[20:23], v142 offset:33792
	ds_read_b128 v[24:27], v142 offset:34816
	ds_read_b128 v[28:31], v142 offset:35840
	ds_read_b128 v[32:35], v142 offset:36864
	ds_read_b128 v[36:39], v142 offset:37888
	ds_read_b128 v[40:43], v142 offset:38912
	ds_read_b128 v[44:47], v142 offset:39936
	s_nop 0
	global_load_lds_dwordx4 v65, s[64:65]
	s_mov_b32 m0, s43
	s_nop 0
	global_load_lds_dwordx4 v64, s[64:65]
	s_and_b64 vcc, exec, s[14:15]
	s_cbranch_vccnz .Lmy_lw_19
	s_waitcnt vmcnt(8)
.Lmy_lw_19:
	s_waitcnt lgkmcnt(0)
	s_barrier
	s_setprio 1
	s_waitcnt lgkmcnt(0)
	v_mfma_scale_f32_16x16x128_f8f6f4 v[124:127], v[0:7], v[16:23], v[124:127], v143, v143 op_sel_hi:[0,0,0]
	v_mfma_scale_f32_16x16x128_f8f6f4 v[120:123], v[8:15], v[16:23], v[120:123], v143, v143 op_sel_hi:[0,0,0]
	v_mfma_scale_f32_16x16x128_f8f6f4 v[112:115], v[0:7], v[24:31], v[112:115], v143, v143 op_sel_hi:[0,0,0]
	v_mfma_scale_f32_16x16x128_f8f6f4 v[104:107], v[8:15], v[24:31], v[104:107], v143, v143 op_sel_hi:[0,0,0]
	v_mfma_scale_f32_16x16x128_f8f6f4 v[96:99], v[0:7], v[32:39], v[96:99], v143, v143 op_sel_hi:[0,0,0]
	v_mfma_scale_f32_16x16x128_f8f6f4 v[88:91], v[8:15], v[32:39], v[130:133], v143, v143 op_sel_hi:[0,0,0]
	v_mfma_scale_f32_16x16x128_f8f6f4 v[80:83], v[0:7], v[40:47], v[208:211], v143, v143 op_sel_hi:[0,0,0]
	v_mfma_scale_f32_16x16x128_f8f6f4 v[72:75], v[8:15], v[40:47], v[212:215], v143, v143 op_sel_hi:[0,0,0]
	s_setprio 0
	s_setprio 1
	v_mfma_scale_f32_16x16x128_f8f6f4 v[116:119], v[144:151], v[16:23], v[116:119], v143, v143 op_sel_hi:[0,0,0]
	v_mfma_scale_f32_16x16x128_f8f6f4 v[108:111], v[152:159], v[16:23], v[108:111], v143, v143 op_sel_hi:[0,0,0]
	v_mfma_scale_f32_16x16x128_f8f6f4 v[100:103], v[144:151], v[24:31], v[100:103], v143, v143 op_sel_hi:[0,0,0]
	v_mfma_scale_f32_16x16x128_f8f6f4 v[92:95], v[152:159], v[24:31], v[176:179], v143, v143 op_sel_hi:[0,0,0]
	v_mfma_scale_f32_16x16x128_f8f6f4 v[84:87], v[144:151], v[32:39], v[180:183], v143, v143 op_sel_hi:[0,0,0]
	v_mfma_scale_f32_16x16x128_f8f6f4 v[76:79], v[152:159], v[32:39], v[184:187], v143, v143 op_sel_hi:[0,0,0]
	v_mfma_scale_f32_16x16x128_f8f6f4 v[68:71], v[144:151], v[40:47], v[188:191], v143, v143 op_sel_hi:[0,0,0]
	v_mfma_scale_f32_16x16x128_f8f6f4 v[64:67], v[152:159], v[40:47], v[192:195], v143, v143 op_sel_hi:[0,0,0]
	s_setprio 0
	s_waitcnt vmcnt(8)
	s_barrier
	s_add_u32 s64, s34, 0x40000
	s_addc_u32 s65, s35, 0
	s_add_i32 s63, s63, s3
	v_mov_b32_e32 v16, v138
	v_mov_b32_e32 v17, v137
	s_mov_b32 m0, s63
	ds_read_b128 v[160:163], v142 offset:49152
	ds_read_b128 v[164:167], v142 offset:50176
	ds_read_b128 v[168:171], v142 offset:51200
	ds_read_b128 v[172:175], v142 offset:52224
	ds_read_b128 v[176:179], v142 offset:53248
	ds_read_b128 v[180:183], v142 offset:54272
	ds_read_b128 v[184:187], v142 offset:55296
	ds_read_b128 v[188:191], v142 offset:56320
	v_mov_b32_e32 v128, v135
	global_load_lds_dwordx4 v17, s[64:65]
	s_add_i32 m0, s63, 0x2000
	s_add_u32 s34, s34, 0x40800
	s_addc_u32 s35, s35, 0
	s_add_i32 s63, s66, s3
	global_load_lds_dwordx4 v16, s[64:65]
	v_mov_b32_e32 v16, v138
	v_mov_b32_e32 v17, v137
	s_mov_b32 m0, s63
	s_nop 0
	global_load_lds_dwordx4 v17, s[34:35]
	s_add_i32 m0, s63, 0x2000
	v_mov_b32_e32 v17, v129
	global_load_lds_dwordx4 v16, s[34:35]
	v_mov_b32_e32 v16, v136
	s_mov_b32 m0, s46
	v_lshl_add_u64 v[18:19], s[30:31], 0, v[128:129]
	v_lshl_add_u64 v[18:19], v[18:19], 0, s[12:13]
	v_lshl_add_u64 v[16:17], s[30:31], 0, v[16:17]
	global_load_lds_dwordx4 v[18:19], off
	v_lshl_add_u64 v[16:17], v[16:17], 0, s[12:13]
	s_mov_b32 m0, s47
	s_nop 0
	global_load_lds_dwordx4 v[16:17], off
	s_and_b64 vcc, exec, s[14:15]
	s_cbranch_vccnz .Lmy_lw_20
	s_waitcnt vmcnt(8)
.Lmy_lw_20:
	s_waitcnt lgkmcnt(0)
	s_barrier
	s_setprio 1
	s_waitcnt lgkmcnt(0)
	v_mfma_scale_f32_16x16x128_f8f6f4 v[60:63], v[0:7], v[160:167], v[60:63], v143, v143 op_sel_hi:[0,0,0]
	v_mfma_scale_f32_16x16x128_f8f6f4 v[56:59], v[8:15], v[160:167], v[56:59], v143, v143 op_sel_hi:[0,0,0]
	v_mfma_scale_f32_16x16x128_f8f6f4 v[48:51], v[0:7], v[168:175], v[48:51], v143, v143 op_sel_hi:[0,0,0]
	v_mfma_scale_f32_16x16x128_f8f6f4 v[40:43], v[8:15], v[168:175], v[196:199], v143, v143 op_sel_hi:[0,0,0]
	v_mfma_scale_f32_16x16x128_f8f6f4 v[32:35], v[0:7], v[176:183], v[200:203], v143, v143 op_sel_hi:[0,0,0]
	v_mfma_scale_f32_16x16x128_f8f6f4 v[24:27], v[8:15], v[176:183], v[204:207], v143, v143 op_sel_hi:[0,0,0]
	v_mfma_scale_f32_16x16x128_f8f6f4 v[16:19], v[0:7], v[184:191], v[216:219], v143, v143 op_sel_hi:[0,0,0]
	v_mfma_scale_f32_16x16x128_f8f6f4 v[8:11], v[8:15], v[184:191], v[220:223], v143, v143 op_sel_hi:[0,0,0]
	s_setprio 0
	s_setprio 1
	v_mfma_scale_f32_16x16x128_f8f6f4 v[52:55], v[144:151], v[160:167], v[52:55], v143, v143 op_sel_hi:[0,0,0]
	v_mfma_scale_f32_16x16x128_f8f6f4 v[44:47], v[152:159], v[160:167], v[224:227], v143, v143 op_sel_hi:[0,0,0]
	v_mfma_scale_f32_16x16x128_f8f6f4 v[36:39], v[144:151], v[168:175], v[228:231], v143, v143 op_sel_hi:[0,0,0]
	v_mfma_scale_f32_16x16x128_f8f6f4 v[28:31], v[152:159], v[168:175], v[232:235], v143, v143 op_sel_hi:[0,0,0]
	v_mfma_scale_f32_16x16x128_f8f6f4 v[20:23], v[144:151], v[176:183], v[236:239], v143, v143 op_sel_hi:[0,0,0]
	v_mfma_scale_f32_16x16x128_f8f6f4 v[12:15], v[152:159], v[176:183], v[240:243], v143, v143 op_sel_hi:[0,0,0]
	v_mfma_scale_f32_16x16x128_f8f6f4 v[4:7], v[144:151], v[184:191], v[244:247], v143, v143 op_sel_hi:[0,0,0]
	v_mfma_scale_f32_16x16x128_f8f6f4 v[0:3], v[152:159], v[184:191], v[248:251], v143, v143 op_sel_hi:[0,0,0]
	s_setprio 0
	s_waitcnt vmcnt(8)
	s_barrier
	s_add_i32 s49, s49, 2
	s_add_u32 s19, s19, 0x80000
	s_addc_u32 s48, s48, 0
	s_add_u32 s28, s28, 0x100
	s_addc_u32 s29, s29, 0
	s_cmp_gt_u32 s49, 13
	s_cbranch_scc0 .LBB0_1751
	s_and_b64 vcc, exec, s[14:15]
	s_cbranch_vccz .LBB0_1754
	s_barrier

.LBB0_1927:
	ds_read_b128 v[162:165], v192
	ds_read_b128 v[166:169], v192 offset:1024
	ds_read_b128 v[170:173], v192 offset:2048
	ds_read_b128 v[174:177], v192 offset:3072
	ds_read_b128 v[178:181], v193
	ds_read_b128 v[182:185], v193 offset:1024
	ds_read_b128 v[196:199], v193 offset:2048
	ds_read_b128 v[200:203], v193 offset:3072
	s_add_u32 s43, s54, 0xfff80080
	s_addc_u32 s48, s55, -1
	s_cmp_eq_u32 s14, 28
	s_cselect_b32 s67, s47, s48
	s_cselect_b32 s66, s46, s43
	s_cselect_b32 s69, s45, s9
	s_cselect_b32 s68, s44, s7
	v_mov_b32_e32 v160, v187
	v_mov_b32_e32 v195, v188
	s_add_i32 m0, s39, 0xc000
	ds_read_b128 v[204:207], v194
	ds_read_b128 v[208:211], v194 offset:1024
	ds_read_b128 v[212:215], v194 offset:2048
	ds_read_b128 v[216:219], v194 offset:3072
	ds_read_b128 v[220:223], v194 offset:4096
	ds_read_b128 v[224:227], v194 offset:5120
	ds_read_b128 v[228:231], v194 offset:6144
	ds_read_b128 v[232:235], v194 offset:7168
	s_nop 0
	global_load_lds_dwordx4 v160, s[54:55]
	s_add_i32 m0, s39, 0xe000
	s_nop 0
	global_load_lds_dwordx4 v195, s[54:55]
	s_and_b64 vcc, exec, s[18:19]
	s_cbranch_vccnz .Lmy_lw_21
	s_waitcnt vmcnt(8)
.Lmy_lw_21:
	s_waitcnt lgkmcnt(0)
	s_barrier
	s_setprio 1
	s_waitcnt lgkmcnt(0)
	v_mfma_f32_16x16x32_bf16 v[156:159], v[162:165], v[204:207], v[156:159]
	v_mfma_f32_16x16x32_bf16 v[152:155], v[170:173], v[204:207], v[152:155]
	v_mfma_f32_16x16x32_bf16 v[140:143], v[162:165], v[212:215], v[140:143]
	v_mfma_f32_16x16x32_bf16 v[136:139], v[170:173], v[212:215], v[136:139]
	v_mfma_f32_16x16x32_bf16 v[124:127], v[162:165], v[220:223], v[124:127]
	v_mfma_f32_16x16x32_bf16 v[120:123], v[170:173], v[220:223], v[120:123]
	v_mfma_f32_16x16x32_bf16 v[108:111], v[162:165], v[228:231], v[108:111]
	v_mfma_f32_16x16x32_bf16 v[104:107], v[170:173], v[228:231], v[104:107]
	v_mfma_f32_16x16x32_bf16 v[156:159], v[166:169], v[208:211], v[156:159]
	v_mfma_f32_16x16x32_bf16 v[152:155], v[174:177], v[208:211], v[152:155]
	v_mfma_f32_16x16x32_bf16 v[140:143], v[166:169], v[216:219], v[140:143]
	v_mfma_f32_16x16x32_bf16 v[136:139], v[174:177], v[216:219], v[136:139]
	v_mfma_f32_16x16x32_bf16 v[124:127], v[166:169], v[224:227], v[124:127]
	v_mfma_f32_16x16x32_bf16 v[120:123], v[174:177], v[224:227], v[120:123]
	v_mfma_f32_16x16x32_bf16 v[108:111], v[166:169], v[232:235], v[108:111]
	v_mfma_f32_16x16x32_bf16 v[104:107], v[174:177], v[232:235], v[104:107]
	s_setprio 0
	s_setprio 1
	v_mfma_f32_16x16x32_bf16 v[148:151], v[178:181], v[204:207], v[148:151]
	v_mfma_f32_16x16x32_bf16 v[144:147], v[196:199], v[204:207], v[144:147]
	v_mfma_f32_16x16x32_bf16 v[132:135], v[178:181], v[212:215], v[132:135]
	v_mfma_f32_16x16x32_bf16 v[128:131], v[196:199], v[212:215], v[128:131]
	v_mfma_f32_16x16x32_bf16 v[116:119], v[178:181], v[220:223], v[116:119]
	v_mfma_f32_16x16x32_bf16 v[112:115], v[196:199], v[220:223], v[112:115]
	v_mfma_f32_16x16x32_bf16 v[100:103], v[178:181], v[228:231], v[100:103]
	v_mfma_f32_16x16x32_bf16 v[96:99], v[196:199], v[228:231], v[96:99]
	v_mfma_f32_16x16x32_bf16 v[148:151], v[182:185], v[208:211], v[148:151]
	v_mfma_f32_16x16x32_bf16 v[144:147], v[200:203], v[208:211], v[144:147]
	v_mfma_f32_16x16x32_bf16 v[132:135], v[182:185], v[216:219], v[132:135]
	v_mfma_f32_16x16x32_bf16 v[128:131], v[200:203], v[216:219], v[128:131]
	v_mfma_f32_16x16x32_bf16 v[116:119], v[182:185], v[224:227], v[116:119]
	v_mfma_f32_16x16x32_bf16 v[112:115], v[200:203], v[224:227], v[112:115]
	v_mfma_f32_16x16x32_bf16 v[100:103], v[182:185], v[232:235], v[100:103]
	v_mfma_f32_16x16x32_bf16 v[96:99], v[200:203], v[232:235], v[96:99]
	s_setprio 0
	s_waitcnt vmcnt(8)
	s_barrier
	s_add_i32 s43, s87, s3
	v_mov_b32_e32 v160, v189
	v_mov_b32_e32 v195, v190
	s_mov_b32 m0, s43
	ds_read_b128 v[204:207], v194 offset:16384
	ds_read_b128 v[208:211], v194 offset:17408
	ds_read_b128 v[212:215], v194 offset:18432
	ds_read_b128 v[216:219], v194 offset:19456
	ds_read_b128 v[220:223], v194 offset:20480
	ds_read_b128 v[224:227], v194 offset:21504
	ds_read_b128 v[228:231], v194 offset:22528
	ds_read_b128 v[232:235], v194 offset:23552
	s_nop 0
	global_load_lds_dwordx4 v160, s[68:69]
	s_add_i32 m0, s43, 0x2000
	s_add_u32 s48, s68, 0x80000
	s_addc_u32 s49, s69, 0
	s_add_i32 s43, s88, s3
	global_load_lds_dwordx4 v195, s[68:69]
	v_mov_b32_e32 v160, v189
	v_mov_b32_e32 v195, v190
	s_mov_b32 m0, s43
	s_nop 0
	global_load_lds_dwordx4 v160, s[48:49]
	s_add_i32 m0, s43, 0x2000
	v_mov_b32_e32 v160, v187
	global_load_lds_dwordx4 v195, s[48:49]
	v_mov_b32_e32 v195, v188
	s_mov_b32 m0, s39
	s_nop 0
	global_load_lds_dwordx4 v160, s[66:67]
	s_mov_b32 m0, s63
	s_nop 0
	global_load_lds_dwordx4 v195, s[66:67]
	s_and_b64 vcc, exec, s[18:19]
	s_cbranch_vccnz .Lmy_lw_22
	s_waitcnt vmcnt(8)
.Lmy_lw_22:
	s_waitcnt lgkmcnt(0)
	s_barrier
	s_setprio 1
	s_waitcnt lgkmcnt(0)
	v_mfma_f32_16x16x32_bf16 v[92:95], v[162:165], v[204:207], v[92:95]
	v_mfma_f32_16x16x32_bf16 v[88:91], v[170:173], v[204:207], v[88:91]
	v_mfma_f32_16x16x32_bf16 v[76:79], v[162:165], v[212:215], v[76:79]
	v_mfma_f32_16x16x32_bf16 v[72:75], v[170:173], v[212:215], v[72:75]
	v_mfma_f32_16x16x32_bf16 v[60:63], v[162:165], v[220:223], v[60:63]
	v_mfma_f32_16x16x32_bf16 v[56:59], v[170:173], v[220:223], v[56:59]
	v_mfma_f32_16x16x32_bf16 v[44:47], v[162:165], v[228:231], v[44:47]
	v_mfma_f32_16x16x32_bf16 v[40:43], v[170:173], v[228:231], v[40:43]
	v_mfma_f32_16x16x32_bf16 v[92:95], v[166:169], v[208:211], v[92:95]
	v_mfma_f32_16x16x32_bf16 v[88:91], v[174:177], v[208:211], v[88:91]
	v_mfma_f32_16x16x32_bf16 v[76:79], v[166:169], v[216:219], v[76:79]
	v_mfma_f32_16x16x32_bf16 v[72:75], v[174:177], v[216:219], v[72:75]
	v_mfma_f32_16x16x32_bf16 v[60:63], v[166:169], v[224:227], v[60:63]
	v_mfma_f32_16x16x32_bf16 v[56:59], v[174:177], v[224:227], v[56:59]
	v_mfma_f32_16x16x32_bf16 v[44:47], v[166:169], v[232:235], v[44:47]
	v_mfma_f32_16x16x32_bf16 v[40:43], v[174:177], v[232:235], v[40:43]
	s_setprio 0
	s_setprio 1
	v_mfma_f32_16x16x32_bf16 v[84:87], v[178:181], v[204:207], v[84:87]
	v_mfma_f32_16x16x32_bf16 v[80:83], v[196:199], v[204:207], v[80:83]
	v_mfma_f32_16x16x32_bf16 v[68:71], v[178:181], v[212:215], v[68:71]
	v_mfma_f32_16x16x32_bf16 v[64:67], v[196:199], v[212:215], v[64:67]
	v_mfma_f32_16x16x32_bf16 v[52:55], v[178:181], v[220:223], v[52:55]
	v_mfma_f32_16x16x32_bf16 v[48:51], v[196:199], v[220:223], v[48:51]
	v_mfma_f32_16x16x32_bf16 v[32:35], v[178:181], v[228:231], v[32:35]
	v_mfma_f32_16x16x32_bf16 v[36:39], v[196:199], v[228:231], v[36:39]
	v_mfma_f32_16x16x32_bf16 v[84:87], v[182:185], v[208:211], v[84:87]
	v_mfma_f32_16x16x32_bf16 v[80:83], v[200:203], v[208:211], v[80:83]
	v_mfma_f32_16x16x32_bf16 v[68:71], v[182:185], v[216:219], v[68:71]
	v_mfma_f32_16x16x32_bf16 v[64:67], v[200:203], v[216:219], v[64:67]
	v_mfma_f32_16x16x32_bf16 v[52:55], v[182:185], v[224:227], v[52:55]
	v_mfma_f32_16x16x32_bf16 v[48:51], v[200:203], v[224:227], v[48:51]
	v_mfma_f32_16x16x32_bf16 v[32:35], v[182:185], v[232:235], v[32:35]
	v_mfma_f32_16x16x32_bf16 v[36:39], v[200:203], v[232:235], v[36:39]
	s_setprio 0
	s_waitcnt vmcnt(8)
	s_barrier
	s_add_i32 s43, 0, 0x18000
	v_add_u32_e32 v160, s43, v191
	s_add_i32 s64, 0, 0x1c000
	ds_read_b128 v[162:165], v160
	ds_read_b128 v[166:169], v160 offset:1024
	ds_read_b128 v[170:173], v160 offset:2048
	ds_read_b128 v[174:177], v160 offset:3072
	v_add_u32_e32 v160, s64, v191
	ds_read_b128 v[178:181], v160
	ds_read_b128 v[182:185], v160 offset:1024
	ds_read_b128 v[196:199], v160 offset:2048
	ds_read_b128 v[200:203], v160 offset:3072
	s_add_u32 s48, s66, 0x80000
	v_mov_b32_e32 v160, v187
	v_mov_b32_e32 v195, v188
	s_addc_u32 s49, s67, 0
	s_mov_b32 m0, s74
	ds_read_b128 v[204:207], v194 offset:32768
	ds_read_b128 v[208:211], v194 offset:33792
	ds_read_b128 v[212:215], v194 offset:34816
	ds_read_b128 v[216:219], v194 offset:35840
	ds_read_b128 v[220:223], v194 offset:36864
	ds_read_b128 v[224:227], v194 offset:37888
	ds_read_b128 v[228:231], v194 offset:38912
	ds_read_b128 v[232:235], v194 offset:39936
	s_nop 0
	global_load_lds_dwordx4 v160, s[48:49]
	s_mov_b32 m0, s75
	s_nop 0
	global_load_lds_dwordx4 v195, s[48:49]
	s_and_b64 vcc, exec, s[18:19]
	s_cbranch_vccnz .Lmy_lw_23
	s_waitcnt vmcnt(8)
.Lmy_lw_23:
	s_waitcnt lgkmcnt(0)
	s_barrier
	s_setprio 1
	s_waitcnt lgkmcnt(0)
	v_mfma_f32_16x16x32_bf16 v[156:159], v[162:165], v[204:207], v[156:159]
	v_mfma_f32_16x16x32_bf16 v[152:155], v[170:173], v[204:207], v[152:155]
	v_mfma_f32_16x16x32_bf16 v[140:143], v[162:165], v[212:215], v[140:143]
	v_mfma_f32_16x16x32_bf16 v[136:139], v[170:173], v[212:215], v[136:139]
	v_mfma_f32_16x16x32_bf16 v[124:127], v[162:165], v[220:223], v[124:127]
	v_mfma_f32_16x16x32_bf16 v[120:123], v[170:173], v[220:223], v[120:123]
	v_mfma_f32_16x16x32_bf16 v[108:111], v[162:165], v[228:231], v[108:111]
	v_mfma_f32_16x16x32_bf16 v[104:107], v[170:173], v[228:231], v[104:107]
	v_mfma_f32_16x16x32_bf16 v[156:159], v[166:169], v[208:211], v[156:159]
	v_mfma_f32_16x16x32_bf16 v[152:155], v[174:177], v[208:211], v[152:155]
	v_mfma_f32_16x16x32_bf16 v[140:143], v[166:169], v[216:219], v[140:143]
	v_mfma_f32_16x16x32_bf16 v[136:139], v[174:177], v[216:219], v[136:139]
	v_mfma_f32_16x16x32_bf16 v[124:127], v[166:169], v[224:227], v[124:127]
	v_mfma_f32_16x16x32_bf16 v[120:123], v[174:177], v[224:227], v[120:123]
	v_mfma_f32_16x16x32_bf16 v[108:111], v[166:169], v[232:235], v[108:111]
	v_mfma_f32_16x16x32_bf16 v[104:107], v[174:177], v[232:235], v[104:107]
	s_setprio 0
	s_setprio 1
	v_mfma_f32_16x16x32_bf16 v[148:151], v[178:181], v[204:207], v[148:151]
	v_mfma_f32_16x16x32_bf16 v[144:147], v[196:199], v[204:207], v[144:147]
	v_mfma_f32_16x16x32_bf16 v[132:135], v[178:181], v[212:215], v[132:135]
	v_mfma_f32_16x16x32_bf16 v[128:131], v[196:199], v[212:215], v[128:131]
	v_mfma_f32_16x16x32_bf16 v[116:119], v[178:181], v[220:223], v[116:119]
	v_mfma_f32_16x16x32_bf16 v[112:115], v[196:199], v[220:223], v[112:115]
	v_mfma_f32_16x16x32_bf16 v[100:103], v[178:181], v[228:231], v[100:103]
	v_mfma_f32_16x16x32_bf16 v[96:99], v[196:199], v[228:231], v[96:99]
	v_mfma_f32_16x16x32_bf16 v[148:151], v[182:185], v[208:211], v[148:151]
	v_mfma_f32_16x16x32_bf16 v[144:147], v[200:203], v[208:211], v[144:147]
	v_mfma_f32_16x16x32_bf16 v[132:135], v[182:185], v[216:219], v[132:135]
	v_mfma_f32_16x16x32_bf16 v[128:131], v[200:203], v[216:219], v[128:131]
	v_mfma_f32_16x16x32_bf16 v[116:119], v[182:185], v[224:227], v[116:119]
	v_mfma_f32_16x16x32_bf16 v[112:115], v[200:203], v[224:227], v[112:115]
	v_mfma_f32_16x16x32_bf16 v[100:103], v[182:185], v[232:235], v[100:103]
	v_mfma_f32_16x16x32_bf16 v[96:99], v[200:203], v[232:235], v[96:99]
	s_setprio 0
	s_waitcnt vmcnt(8)
	s_barrier
	v_mov_b32_e32 v160, v189
	v_mov_b32_e32 v236, v190
	ds_read_b128 v[204:207], v194 offset:49152
	ds_read_b128 v[208:211], v194 offset:50176
	ds_read_b128 v[212:215], v194 offset:51200
	ds_read_b128 v[216:219], v194 offset:52224
	ds_read_b128 v[220:223], v194 offset:53248
	ds_read_b128 v[224:227], v194 offset:54272
	ds_read_b128 v[228:231], v194 offset:55296
	ds_read_b128 v[232:235], v194 offset:56320
	s_add_i32 s43, s43, s3
	v_lshl_add_u64 v[238:239], s[68:69], 0, v[160:161]
	v_lshl_add_u64 v[238:239], v[238:239], 0, s[16:17]
	s_mov_b32 m0, s43
	v_mov_b32_e32 v237, v161
	global_load_lds_dwordx4 v[238:239], off
	s_add_i32 m0, s43, 0x2000
	v_lshl_add_u64 v[236:237], s[68:69], 0, v[236:237]
	s_add_u32 s48, s68, 0x80080
	v_lshl_add_u64 v[236:237], v[236:237], 0, s[16:17]
	v_mov_b32_e32 v160, v189
	v_mov_b32_e32 v195, v190
	s_addc_u32 s49, s69, 0
	s_add_i32 s43, s64, s3
	global_load_lds_dwordx4 v[236:237], off
	s_mov_b32 m0, s43
	v_mov_b32_e32 v236, v188
	global_load_lds_dwordx4 v160, s[48:49]
	s_add_i32 m0, s43, 0x2000
	v_mov_b32_e32 v160, v187
	global_load_lds_dwordx4 v195, s[48:49]
	v_mov_b32_e32 v237, v161
	v_lshl_add_u64 v[238:239], s[66:67], 0, v[160:161]
	v_lshl_add_u64 v[238:239], v[238:239], 0, s[16:17]
	s_mov_b32 m0, s79
	v_lshl_add_u64 v[236:237], s[66:67], 0, v[236:237]
	global_load_lds_dwordx4 v[238:239], off
	v_lshl_add_u64 v[236:237], v[236:237], 0, s[16:17]
	s_mov_b32 m0, s80
	s_nop 0
	global_load_lds_dwordx4 v[236:237], off
	s_and_b64 vcc, exec, s[18:19]
	s_cbranch_vccnz .Lmy_lw_24
	s_waitcnt vmcnt(8)
.Lmy_lw_24:
	s_waitcnt lgkmcnt(0)
	s_barrier
	s_setprio 1
	s_waitcnt lgkmcnt(0)
	v_mfma_f32_16x16x32_bf16 v[92:95], v[162:165], v[204:207], v[92:95]
	v_mfma_f32_16x16x32_bf16 v[88:91], v[170:173], v[204:207], v[88:91]
	v_mfma_f32_16x16x32_bf16 v[76:79], v[162:165], v[212:215], v[76:79]
	v_mfma_f32_16x16x32_bf16 v[72:75], v[170:173], v[212:215], v[72:75]
	v_mfma_f32_16x16x32_bf16 v[60:63], v[162:165], v[220:223], v[60:63]
	v_mfma_f32_16x16x32_bf16 v[56:59], v[170:173], v[220:223], v[56:59]
	v_mfma_f32_16x16x32_bf16 v[44:47], v[162:165], v[228:231], v[44:47]
	v_mfma_f32_16x16x32_bf16 v[40:43], v[170:173], v[228:231], v[40:43]
	v_mfma_f32_16x16x32_bf16 v[92:95], v[166:169], v[208:211], v[92:95]
	v_mfma_f32_16x16x32_bf16 v[88:91], v[174:177], v[208:211], v[88:91]
	v_mfma_f32_16x16x32_bf16 v[76:79], v[166:169], v[216:219], v[76:79]
	v_mfma_f32_16x16x32_bf16 v[72:75], v[174:177], v[216:219], v[72:75]
	v_mfma_f32_16x16x32_bf16 v[60:63], v[166:169], v[224:227], v[60:63]
	v_mfma_f32_16x16x32_bf16 v[56:59], v[174:177], v[224:227], v[56:59]
	v_mfma_f32_16x16x32_bf16 v[44:47], v[166:169], v[232:235], v[44:47]
	v_mfma_f32_16x16x32_bf16 v[40:43], v[174:177], v[232:235], v[40:43]
	s_setprio 0
	s_setprio 1
	v_mfma_f32_16x16x32_bf16 v[84:87], v[178:181], v[204:207], v[84:87]
	v_mfma_f32_16x16x32_bf16 v[80:83], v[196:199], v[204:207], v[80:83]
	v_mfma_f32_16x16x32_bf16 v[68:71], v[178:181], v[212:215], v[68:71]
	v_mfma_f32_16x16x32_bf16 v[64:67], v[196:199], v[212:215], v[64:67]
	v_mfma_f32_16x16x32_bf16 v[52:55], v[178:181], v[220:223], v[52:55]
	v_mfma_f32_16x16x32_bf16 v[48:51], v[196:199], v[220:223], v[48:51]
	v_mfma_f32_16x16x32_bf16 v[32:35], v[178:181], v[228:231], v[32:35]
	v_mfma_f32_16x16x32_bf16 v[36:39], v[196:199], v[228:231], v[36:39]
	v_mfma_f32_16x16x32_bf16 v[84:87], v[182:185], v[208:211], v[84:87]
	v_mfma_f32_16x16x32_bf16 v[80:83], v[200:203], v[208:211], v[80:83]
	v_mfma_f32_16x16x32_bf16 v[68:71], v[182:185], v[216:219], v[68:71]
	v_mfma_f32_16x16x32_bf16 v[64:67], v[200:203], v[216:219], v[64:67]
	v_mfma_f32_16x16x32_bf16 v[52:55], v[182:185], v[224:227], v[52:55]
	v_mfma_f32_16x16x32_bf16 v[48:51], v[200:203], v[224:227], v[48:51]
	v_mfma_f32_16x16x32_bf16 v[32:35], v[182:185], v[232:235], v[32:35]
	v_mfma_f32_16x16x32_bf16 v[36:39], v[200:203], v[232:235], v[36:39]
	s_setprio 0
	s_waitcnt vmcnt(8)
	s_barrier
	s_add_i32 s14, s14, 2
	s_add_u32 s54, s54, 0x100
	s_addc_u32 s55, s55, 0
	s_add_u32 s7, s7, 0x100
	s_addc_u32 s9, s9, 0
	s_cmp_gt_u32 s14, 29
	s_cbranch_scc0 .LBB0_1927
	s_and_b64 vcc, exec, s[18:19]
	s_cbranch_vccz .LBB0_1930
	s_barrier

.LBB0_2487:
	ds_read_b128 v[130:133], v146
	ds_read_b128 v[134:137], v146 offset:1024
	ds_read_b128 v[150:153], v146 offset:2048
	ds_read_b128 v[154:157], v146 offset:3072
	ds_read_b128 v[158:161], v147
	ds_read_b128 v[162:165], v147 offset:1024
	ds_read_b128 v[166:169], v147 offset:2048
	ds_read_b128 v[170:173], v147 offset:3072
	s_add_u32 s42, s40, 0xfffc0080
	s_addc_u32 s43, s41, -1
	s_cmp_eq_u32 s49, 12
	s_cselect_b32 s43, s31, s43
	s_cselect_b32 s42, s30, s42
	s_cselect_b32 s45, s35, s48
	s_cselect_b32 s44, s34, s29
	v_mov_b32_e32 v128, v142
	v_mov_b32_e32 v138, v141
	s_add_i32 m0, s47, 0xc000
	ds_read_b128 v[174:177], v148
	ds_read_b128 v[178:181], v148 offset:1024
	ds_read_b128 v[182:185], v148 offset:2048
	ds_read_b128 v[186:189], v148 offset:3072
	ds_read_b128 v[190:193], v148 offset:4096
	ds_read_b128 v[194:197], v148 offset:5120
	ds_read_b128 v[198:201], v148 offset:6144
	ds_read_b128 v[202:205], v148 offset:7168
	s_nop 0
	global_load_lds_dwordx4 v138, s[40:41]
	s_add_i32 m0, s47, 0xe000
	s_nop 0
	global_load_lds_dwordx4 v128, s[40:41]
	s_and_b64 vcc, exec, s[16:17]
	s_cbranch_vccnz .Lmy_lw_25
	s_waitcnt vmcnt(8)
.Lmy_lw_25:
	s_waitcnt lgkmcnt(0)
	s_barrier
	s_setprio 1
	s_waitcnt lgkmcnt(0)
	v_mfma_scale_f32_16x16x128_f8f6f4 v[124:127], v[130:137], v[174:181], v[124:127], v149, v149 op_sel_hi:[0,0,0]
	v_mfma_scale_f32_16x16x128_f8f6f4 v[120:123], v[150:157], v[174:181], v[120:123], v149, v149 op_sel_hi:[0,0,0]
	v_mfma_scale_f32_16x16x128_f8f6f4 v[108:111], v[130:137], v[182:189], v[108:111], v149, v149 op_sel_hi:[0,0,0]
	v_mfma_scale_f32_16x16x128_f8f6f4 v[104:107], v[150:157], v[182:189], v[104:107], v149, v149 op_sel_hi:[0,0,0]
	v_mfma_scale_f32_16x16x128_f8f6f4 v[206:209], v[130:137], v[190:197], v[92:95], v149, v149 op_sel_hi:[0,0,0]
	v_mfma_scale_f32_16x16x128_f8f6f4 v[210:213], v[150:157], v[190:197], v[88:91], v149, v149 op_sel_hi:[0,0,0]
	v_mfma_scale_f32_16x16x128_f8f6f4 v[214:217], v[130:137], v[198:205], v[76:79], v149, v149 op_sel_hi:[0,0,0]
	v_mfma_scale_f32_16x16x128_f8f6f4 v[218:221], v[150:157], v[198:205], v[72:75], v149, v149 op_sel_hi:[0,0,0]
	s_setprio 0
	s_setprio 1
	v_mfma_scale_f32_16x16x128_f8f6f4 v[116:119], v[158:165], v[174:181], v[116:119], v149, v149 op_sel_hi:[0,0,0]
	v_mfma_scale_f32_16x16x128_f8f6f4 v[112:115], v[166:173], v[174:181], v[112:115], v149, v149 op_sel_hi:[0,0,0]
	v_mfma_scale_f32_16x16x128_f8f6f4 v[100:103], v[158:165], v[182:189], v[100:103], v149, v149 op_sel_hi:[0,0,0]
	v_mfma_scale_f32_16x16x128_f8f6f4 v[96:99], v[166:173], v[182:189], v[96:99], v149, v149 op_sel_hi:[0,0,0]
	v_mfma_scale_f32_16x16x128_f8f6f4 v[174:177], v[158:165], v[190:197], v[84:87], v149, v149 op_sel_hi:[0,0,0]
	v_mfma_scale_f32_16x16x128_f8f6f4 v[178:181], v[166:173], v[190:197], v[80:83], v149, v149 op_sel_hi:[0,0,0]
	v_mfma_scale_f32_16x16x128_f8f6f4 v[182:185], v[158:165], v[198:205], v[68:71], v149, v149 op_sel_hi:[0,0,0]
	v_mfma_scale_f32_16x16x128_f8f6f4 v[186:189], v[166:173], v[198:205], v[64:67], v149, v149 op_sel_hi:[0,0,0]
	s_setprio 0
	s_waitcnt vmcnt(8)
	s_barrier
	s_add_i32 s64, s67, s3
	v_mov_b32_e32 v128, v144
	v_mov_b32_e32 v138, v143
	s_mov_b32 m0, s64
	s_nop 0
	ds_read_b128 v[64:67], v148 offset:16384
	ds_read_b128 v[68:71], v148 offset:17408
	ds_read_b128 v[72:75], v148 offset:18432
	ds_read_b128 v[76:79], v148 offset:19456
	ds_read_b128 v[80:83], v148 offset:20480
	ds_read_b128 v[84:87], v148 offset:21504
	ds_read_b128 v[88:91], v148 offset:22528
	ds_read_b128 v[92:95], v148 offset:23552
	v_mov_b32_e32 v139, v129
	global_load_lds_dwordx4 v138, s[44:45]
	s_add_i32 m0, s64, 0x2000
	v_mov_b32_e32 v138, v144
	global_load_lds_dwordx4 v128, s[44:45]
	v_mov_b32_e32 v128, v143
	s_add_i32 s64, s68, s3
	v_lshl_add_u64 v[190:191], s[44:45], 0, v[128:129]
	v_lshl_add_u64 v[190:191], v[190:191], 0, s[10:11]
	s_mov_b32 m0, s64
	v_lshl_add_u64 v[138:139], s[44:45], 0, v[138:139]
	global_load_lds_dwordx4 v[190:191], off
	v_lshl_add_u64 v[138:139], v[138:139], 0, s[10:11]
	s_add_i32 m0, s64, 0x2000
	v_mov_b32_e32 v128, v142
	global_load_lds_dwordx4 v[138:139], off
	v_mov_b32_e32 v138, v141
	s_mov_b32 m0, s47
	s_nop 0
	global_load_lds_dwordx4 v138, s[42:43]
	s_mov_b32 m0, s50
	s_nop 0
	global_load_lds_dwordx4 v128, s[42:43]
	s_and_b64 vcc, exec, s[16:17]
	s_cbranch_vccnz .Lmy_lw_26
	s_waitcnt vmcnt(8)
.Lmy_lw_26:
	s_waitcnt lgkmcnt(0)
	s_barrier
	s_setprio 1
	s_waitcnt lgkmcnt(0)
	v_mfma_scale_f32_16x16x128_f8f6f4 v[60:63], v[130:137], v[64:71], v[60:63], v149, v149 op_sel_hi:[0,0,0]
	v_mfma_scale_f32_16x16x128_f8f6f4 v[56:59], v[150:157], v[64:71], v[56:59], v149, v149 op_sel_hi:[0,0,0]
	v_mfma_scale_f32_16x16x128_f8f6f4 v[190:193], v[130:137], v[72:79], v[44:47], v149, v149 op_sel_hi:[0,0,0]
	v_mfma_scale_f32_16x16x128_f8f6f4 v[194:197], v[150:157], v[72:79], v[40:43], v149, v149 op_sel_hi:[0,0,0]
	v_mfma_scale_f32_16x16x128_f8f6f4 v[198:201], v[130:137], v[80:87], v[28:31], v149, v149 op_sel_hi:[0,0,0]
	v_mfma_scale_f32_16x16x128_f8f6f4 v[202:205], v[150:157], v[80:87], v[24:27], v149, v149 op_sel_hi:[0,0,0]
	v_mfma_scale_f32_16x16x128_f8f6f4 v[222:225], v[130:137], v[88:95], v[12:15], v149, v149 op_sel_hi:[0,0,0]
	v_mfma_scale_f32_16x16x128_f8f6f4 v[226:229], v[150:157], v[88:95], v[8:11], v149, v149 op_sel_hi:[0,0,0]
	s_setprio 0
	s_setprio 1
	v_mfma_scale_f32_16x16x128_f8f6f4 v[52:55], v[158:165], v[64:71], v[52:55], v149, v149 op_sel_hi:[0,0,0]
	v_mfma_scale_f32_16x16x128_f8f6f4 v[48:51], v[166:173], v[64:71], v[48:51], v149, v149 op_sel_hi:[0,0,0]
	v_mfma_scale_f32_16x16x128_f8f6f4 v[230:233], v[158:165], v[72:79], v[36:39], v149, v149 op_sel_hi:[0,0,0]
	v_mfma_scale_f32_16x16x128_f8f6f4 v[234:237], v[166:173], v[72:79], v[32:35], v149, v149 op_sel_hi:[0,0,0]
	v_mfma_scale_f32_16x16x128_f8f6f4 v[238:241], v[158:165], v[80:87], v[20:23], v149, v149 op_sel_hi:[0,0,0]
	v_mfma_scale_f32_16x16x128_f8f6f4 v[242:245], v[166:173], v[80:87], v[16:19], v149, v149 op_sel_hi:[0,0,0]
	v_mfma_scale_f32_16x16x128_f8f6f4 v[246:249], v[158:165], v[88:95], v[4:7], v149, v149 op_sel_hi:[0,0,0]
	v_mfma_scale_f32_16x16x128_f8f6f4 v[250:253], v[166:173], v[88:95], v[0:3], v149, v149 op_sel_hi:[0,0,0]
	s_setprio 0
	s_waitcnt vmcnt(8)
	s_barrier
	s_add_i32 s73, 0, 0x18000
	v_add_u32_e32 v8, s73, v145
	s_add_i32 s74, 0, 0x1c000
	s_nop 1
	ds_read_b128 v[0:3], v8
	ds_read_b128 v[4:7], v8 offset:1024
	ds_read_b128 v[16:19], v8 offset:2048
	ds_read_b128 v[20:23], v8 offset:3072
	v_add_u32_e32 v8, s74, v145
	ds_read_b128 v[130:133], v8
	ds_read_b128 v[134:137], v8 offset:1024
	ds_read_b128 v[150:153], v8 offset:2048
	ds_read_b128 v[154:157], v8 offset:3072
	s_add_u32 s64, s42, 0x40000
	v_mov_b32_e32 v64, v142
	v_mov_b32_e32 v65, v141
	s_addc_u32 s65, s43, 0
	s_mov_b32 m0, s51
	ds_read_b128 v[8:11], v148 offset:32768
	ds_read_b128 v[12:15], v148 offset:33792
	ds_read_b128 v[24:27], v148 offset:34816
	ds_read_b128 v[28:31], v148 offset:35840
	ds_read_b128 v[32:35], v148 offset:36864
	ds_read_b128 v[36:39], v148 offset:37888
	ds_read_b128 v[40:43], v148 offset:38912
	ds_read_b128 v[44:47], v148 offset:39936
	s_nop 0
	global_load_lds_dwordx4 v65, s[64:65]
	s_mov_b32 m0, s52
	s_nop 0
	global_load_lds_dwordx4 v64, s[64:65]
	s_and_b64 vcc, exec, s[16:17]
	s_cbranch_vccnz .Lmy_lw_27
	s_waitcnt vmcnt(8)
.Lmy_lw_27:
	s_waitcnt lgkmcnt(0)
	s_barrier
	s_setprio 1
	s_waitcnt lgkmcnt(0)
	v_mfma_scale_f32_16x16x128_f8f6f4 v[124:127], v[0:7], v[8:15], v[124:127], v149, v149 op_sel_hi:[0,0,0]
	v_mfma_scale_f32_16x16x128_f8f6f4 v[120:123], v[16:23], v[8:15], v[120:123], v149, v149 op_sel_hi:[0,0,0]
	v_mfma_scale_f32_16x16x128_f8f6f4 v[108:111], v[0:7], v[24:31], v[108:111], v149, v149 op_sel_hi:[0,0,0]
	v_mfma_scale_f32_16x16x128_f8f6f4 v[104:107], v[16:23], v[24:31], v[104:107], v149, v149 op_sel_hi:[0,0,0]
	v_mfma_scale_f32_16x16x128_f8f6f4 v[92:95], v[0:7], v[32:39], v[206:209], v149, v149 op_sel_hi:[0,0,0]
	v_mfma_scale_f32_16x16x128_f8f6f4 v[88:91], v[16:23], v[32:39], v[210:213], v149, v149 op_sel_hi:[0,0,0]
	v_mfma_scale_f32_16x16x128_f8f6f4 v[76:79], v[0:7], v[40:47], v[214:217], v149, v149 op_sel_hi:[0,0,0]
	v_mfma_scale_f32_16x16x128_f8f6f4 v[72:75], v[16:23], v[40:47], v[218:221], v149, v149 op_sel_hi:[0,0,0]
	s_setprio 0
	s_setprio 1
	v_mfma_scale_f32_16x16x128_f8f6f4 v[116:119], v[130:137], v[8:15], v[116:119], v149, v149 op_sel_hi:[0,0,0]
	v_mfma_scale_f32_16x16x128_f8f6f4 v[112:115], v[150:157], v[8:15], v[112:115], v149, v149 op_sel_hi:[0,0,0]
	v_mfma_scale_f32_16x16x128_f8f6f4 v[100:103], v[130:137], v[24:31], v[100:103], v149, v149 op_sel_hi:[0,0,0]
	v_mfma_scale_f32_16x16x128_f8f6f4 v[96:99], v[150:157], v[24:31], v[96:99], v149, v149 op_sel_hi:[0,0,0]
	v_mfma_scale_f32_16x16x128_f8f6f4 v[84:87], v[130:137], v[32:39], v[174:177], v149, v149 op_sel_hi:[0,0,0]
	v_mfma_scale_f32_16x16x128_f8f6f4 v[80:83], v[150:157], v[32:39], v[178:181], v149, v149 op_sel_hi:[0,0,0]
	v_mfma_scale_f32_16x16x128_f8f6f4 v[68:71], v[130:137], v[40:47], v[182:185], v149, v149 op_sel_hi:[0,0,0]
	v_mfma_scale_f32_16x16x128_f8f6f4 v[64:67], v[150:157], v[40:47], v[186:189], v149, v149 op_sel_hi:[0,0,0]
	s_setprio 0
	s_waitcnt vmcnt(8)
	s_barrier
	s_add_u32 s64, s44, 0x40000
	s_addc_u32 s65, s45, 0
	s_add_i32 s73, s73, s3
	v_mov_b32_e32 v8, v144
	v_mov_b32_e32 v9, v143
	s_mov_b32 m0, s73
	ds_read_b128 v[32:35], v148 offset:49152
	ds_read_b128 v[36:39], v148 offset:50176
	ds_read_b128 v[158:161], v148 offset:51200
	ds_read_b128 v[162:165], v148 offset:52224
	ds_read_b128 v[166:169], v148 offset:53248
	ds_read_b128 v[170:173], v148 offset:54272
	ds_read_b128 v[174:177], v148 offset:55296
	ds_read_b128 v[178:181], v148 offset:56320
	v_mov_b32_e32 v128, v141
	global_load_lds_dwordx4 v9, s[64:65]
	s_add_i32 m0, s73, 0x2000
	s_add_u32 s44, s44, 0x40800
	global_load_lds_dwordx4 v8, s[64:65]
	s_addc_u32 s45, s45, 0
	s_add_i32 s64, s74, s3
	v_mov_b32_e32 v8, v144
	v_mov_b32_e32 v9, v143
	s_mov_b32 m0, s64
	s_nop 0
	global_load_lds_dwordx4 v9, s[44:45]
	s_add_i32 m0, s64, 0x2000
	v_mov_b32_e32 v9, v129
	global_load_lds_dwordx4 v8, s[44:45]
	v_mov_b32_e32 v8, v142
	s_mov_b32 m0, s55
	v_lshl_add_u64 v[10:11], s[42:43], 0, v[128:129]
	v_lshl_add_u64 v[10:11], v[10:11], 0, s[14:15]
	v_lshl_add_u64 v[8:9], s[42:43], 0, v[8:9]
	global_load_lds_dwordx4 v[10:11], off
	v_lshl_add_u64 v[8:9], v[8:9], 0, s[14:15]
	s_mov_b32 m0, s63
	s_nop 0
	global_load_lds_dwordx4 v[8:9], off
	s_and_b64 vcc, exec, s[16:17]
	s_cbranch_vccnz .Lmy_lw_28
	s_waitcnt vmcnt(8)
.Lmy_lw_28:
	s_waitcnt lgkmcnt(0)
	s_barrier
	s_setprio 1
	s_waitcnt lgkmcnt(0)
	v_mfma_scale_f32_16x16x128_f8f6f4 v[60:63], v[0:7], v[32:39], v[60:63], v149, v149 op_sel_hi:[0,0,0]
	v_mfma_scale_f32_16x16x128_f8f6f4 v[56:59], v[16:23], v[32:39], v[56:59], v149, v149 op_sel_hi:[0,0,0]
	v_mfma_scale_f32_16x16x128_f8f6f4 v[44:47], v[0:7], v[158:165], v[190:193], v149, v149 op_sel_hi:[0,0,0]
	v_mfma_scale_f32_16x16x128_f8f6f4 v[40:43], v[16:23], v[158:165], v[194:197], v149, v149 op_sel_hi:[0,0,0]
	v_mfma_scale_f32_16x16x128_f8f6f4 v[28:31], v[0:7], v[166:173], v[198:201], v149, v149 op_sel_hi:[0,0,0]
	v_mfma_scale_f32_16x16x128_f8f6f4 v[24:27], v[16:23], v[166:173], v[202:205], v149, v149 op_sel_hi:[0,0,0]
	v_mfma_scale_f32_16x16x128_f8f6f4 v[12:15], v[0:7], v[174:181], v[222:225], v149, v149 op_sel_hi:[0,0,0]
	v_mfma_scale_f32_16x16x128_f8f6f4 v[8:11], v[16:23], v[174:181], v[226:229], v149, v149 op_sel_hi:[0,0,0]
	s_setprio 0
	s_setprio 1
	v_mfma_scale_f32_16x16x128_f8f6f4 v[52:55], v[130:137], v[32:39], v[52:55], v149, v149 op_sel_hi:[0,0,0]
	v_mfma_scale_f32_16x16x128_f8f6f4 v[48:51], v[150:157], v[32:39], v[48:51], v149, v149 op_sel_hi:[0,0,0]
	v_mfma_scale_f32_16x16x128_f8f6f4 v[36:39], v[130:137], v[158:165], v[230:233], v149, v149 op_sel_hi:[0,0,0]
	v_mfma_scale_f32_16x16x128_f8f6f4 v[32:35], v[150:157], v[158:165], v[234:237], v149, v149 op_sel_hi:[0,0,0]
	v_mfma_scale_f32_16x16x128_f8f6f4 v[20:23], v[130:137], v[166:173], v[238:241], v149, v149 op_sel_hi:[0,0,0]
	v_mfma_scale_f32_16x16x128_f8f6f4 v[16:19], v[150:157], v[166:173], v[242:245], v149, v149 op_sel_hi:[0,0,0]
	v_mfma_scale_f32_16x16x128_f8f6f4 v[4:7], v[130:137], v[174:181], v[246:249], v149, v149 op_sel_hi:[0,0,0]
	v_mfma_scale_f32_16x16x128_f8f6f4 v[0:3], v[150:157], v[174:181], v[250:253], v149, v149 op_sel_hi:[0,0,0]
	s_setprio 0
	s_waitcnt vmcnt(8)
	s_barrier
	s_add_i32 s49, s49, 2
	s_add_u32 s29, s29, 0x80000
	s_addc_u32 s48, s48, 0
	s_add_u32 s40, s40, 0x100
	s_addc_u32 s41, s41, 0
	s_cmp_gt_u32 s49, 13
	s_cbranch_scc0 .LBB0_2487
	s_and_b64 vcc, exec, s[16:17]
	s_cbranch_vccz .LBB0_2490
	s_barrier

.LBB0_2964:
	ds_read_b128 v[144:147], v140
	ds_read_b128 v[148:151], v140 offset:1024
	ds_read_b128 v[152:155], v140 offset:2048
	ds_read_b128 v[156:159], v140 offset:3072
	ds_read_b128 v[160:163], v141
	ds_read_b128 v[164:167], v141 offset:1024
	ds_read_b128 v[168:171], v141 offset:2048
	ds_read_b128 v[172:175], v141 offset:3072
	s_add_u32 s30, s28, 0xfffc0080
	s_addc_u32 s31, s29, -1
	s_cmp_eq_u32 s53, 12
	s_cselect_b32 s31, s21, s31
	s_cselect_b32 s30, s20, s30
	s_cselect_b32 s35, s23, s52
	s_cselect_b32 s34, s22, s19
	v_mov_b32_e32 v128, v135
	v_mov_b32_e32 v130, v136
	s_add_i32 m0, s40, 0xc000
	ds_read_b128 v[176:179], v142
	ds_read_b128 v[180:183], v142 offset:1024
	ds_read_b128 v[184:187], v142 offset:2048
	ds_read_b128 v[188:191], v142 offset:3072
	ds_read_b128 v[192:195], v142 offset:4096
	ds_read_b128 v[196:199], v142 offset:5120
	ds_read_b128 v[200:203], v142 offset:6144
	ds_read_b128 v[204:207], v142 offset:7168
	s_nop 0
	global_load_lds_dwordx4 v128, s[28:29]
	s_add_i32 m0, s40, 0xe000
	s_nop 0
	global_load_lds_dwordx4 v130, s[28:29]
	s_and_b64 vcc, exec, s[14:15]
	s_cbranch_vccnz .Lmy_lw_33
	s_waitcnt vmcnt(8)
.Lmy_lw_33:
	s_waitcnt lgkmcnt(0)
	s_barrier
	s_setprio 1
	s_waitcnt lgkmcnt(0)
	v_mfma_scale_f32_16x16x128_f8f6f4 v[124:127], v[144:151], v[176:183], v[124:127], v143, v143 op_sel_hi:[0,0,0]
	v_mfma_scale_f32_16x16x128_f8f6f4 v[120:123], v[152:159], v[176:183], v[120:123], v143, v143 op_sel_hi:[0,0,0]
	v_mfma_scale_f32_16x16x128_f8f6f4 v[112:115], v[144:151], v[184:191], v[112:115], v143, v143 op_sel_hi:[0,0,0]
	v_mfma_scale_f32_16x16x128_f8f6f4 v[104:107], v[152:159], v[184:191], v[104:107], v143, v143 op_sel_hi:[0,0,0]
	v_mfma_scale_f32_16x16x128_f8f6f4 v[96:99], v[144:151], v[192:199], v[96:99], v143, v143 op_sel_hi:[0,0,0]
	v_mfma_scale_f32_16x16x128_f8f6f4 v[130:133], v[152:159], v[192:199], v[88:91], v143, v143 op_sel_hi:[0,0,0]
	v_mfma_scale_f32_16x16x128_f8f6f4 v[208:211], v[144:151], v[200:207], v[80:83], v143, v143 op_sel_hi:[0,0,0]
	v_mfma_scale_f32_16x16x128_f8f6f4 v[212:215], v[152:159], v[200:207], v[72:75], v143, v143 op_sel_hi:[0,0,0]
	s_setprio 0
	s_setprio 1
	v_mfma_scale_f32_16x16x128_f8f6f4 v[116:119], v[160:167], v[176:183], v[116:119], v143, v143 op_sel_hi:[0,0,0]
	v_mfma_scale_f32_16x16x128_f8f6f4 v[108:111], v[168:175], v[176:183], v[108:111], v143, v143 op_sel_hi:[0,0,0]
	v_mfma_scale_f32_16x16x128_f8f6f4 v[100:103], v[160:167], v[184:191], v[100:103], v143, v143 op_sel_hi:[0,0,0]
	v_mfma_scale_f32_16x16x128_f8f6f4 v[176:179], v[168:175], v[184:191], v[92:95], v143, v143 op_sel_hi:[0,0,0]
	v_mfma_scale_f32_16x16x128_f8f6f4 v[180:183], v[160:167], v[192:199], v[84:87], v143, v143 op_sel_hi:[0,0,0]
	v_mfma_scale_f32_16x16x128_f8f6f4 v[184:187], v[168:175], v[192:199], v[76:79], v143, v143 op_sel_hi:[0,0,0]
	v_mfma_scale_f32_16x16x128_f8f6f4 v[188:191], v[160:167], v[200:207], v[68:71], v143, v143 op_sel_hi:[0,0,0]
	v_mfma_scale_f32_16x16x128_f8f6f4 v[192:195], v[168:175], v[200:207], v[64:67], v143, v143 op_sel_hi:[0,0,0]
	s_setprio 0
	s_waitcnt vmcnt(8)
	s_barrier
	s_add_i32 s54, s49, s3
	v_mov_b32_e32 v128, v137
	v_mov_b32_e32 v196, v138
	s_mov_b32 m0, s54
	s_nop 0
	ds_read_b128 v[64:67], v142 offset:16384
	ds_read_b128 v[68:71], v142 offset:17408
	ds_read_b128 v[72:75], v142 offset:18432
	ds_read_b128 v[76:79], v142 offset:19456
	ds_read_b128 v[80:83], v142 offset:20480
	ds_read_b128 v[84:87], v142 offset:21504
	ds_read_b128 v[88:91], v142 offset:22528
	ds_read_b128 v[92:95], v142 offset:23552
	v_mov_b32_e32 v197, v129
	global_load_lds_dwordx4 v128, s[34:35]
	s_add_i32 m0, s54, 0x2000
	v_mov_b32_e32 v128, v137
	global_load_lds_dwordx4 v196, s[34:35]
	v_mov_b32_e32 v196, v138
	s_add_i32 s54, s50, s3
	v_lshl_add_u64 v[198:199], s[34:35], 0, v[128:129]
	v_lshl_add_u64 v[198:199], v[198:199], 0, s[8:9]
	s_mov_b32 m0, s54
	v_lshl_add_u64 v[196:197], s[34:35], 0, v[196:197]
	global_load_lds_dwordx4 v[198:199], off
	v_lshl_add_u64 v[196:197], v[196:197], 0, s[8:9]
	s_add_i32 m0, s54, 0x2000
	v_mov_b32_e32 v128, v135
	global_load_lds_dwordx4 v[196:197], off
	v_mov_b32_e32 v196, v136
	s_mov_b32 m0, s40
	s_nop 0
	global_load_lds_dwordx4 v128, s[30:31]
	s_mov_b32 m0, s41
	s_nop 0
	global_load_lds_dwordx4 v196, s[30:31]
	s_and_b64 vcc, exec, s[14:15]
	s_cbranch_vccnz .Lmy_lw_34
	s_waitcnt vmcnt(8)
.Lmy_lw_34:
	s_waitcnt lgkmcnt(0)
	s_barrier
	s_setprio 1
	s_waitcnt lgkmcnt(0)
	v_mfma_scale_f32_16x16x128_f8f6f4 v[60:63], v[144:151], v[64:71], v[60:63], v143, v143 op_sel_hi:[0,0,0]
	v_mfma_scale_f32_16x16x128_f8f6f4 v[56:59], v[152:159], v[64:71], v[56:59], v143, v143 op_sel_hi:[0,0,0]
	v_mfma_scale_f32_16x16x128_f8f6f4 v[48:51], v[144:151], v[72:79], v[48:51], v143, v143 op_sel_hi:[0,0,0]
	v_mfma_scale_f32_16x16x128_f8f6f4 v[196:199], v[152:159], v[72:79], v[40:43], v143, v143 op_sel_hi:[0,0,0]
	v_mfma_scale_f32_16x16x128_f8f6f4 v[200:203], v[144:151], v[80:87], v[32:35], v143, v143 op_sel_hi:[0,0,0]
	v_mfma_scale_f32_16x16x128_f8f6f4 v[204:207], v[152:159], v[80:87], v[24:27], v143, v143 op_sel_hi:[0,0,0]
	v_mfma_scale_f32_16x16x128_f8f6f4 v[216:219], v[144:151], v[88:95], v[16:19], v143, v143 op_sel_hi:[0,0,0]
	v_mfma_scale_f32_16x16x128_f8f6f4 v[220:223], v[152:159], v[88:95], v[8:11], v143, v143 op_sel_hi:[0,0,0]
	s_setprio 0
	s_setprio 1
	v_mfma_scale_f32_16x16x128_f8f6f4 v[52:55], v[160:167], v[64:71], v[52:55], v143, v143 op_sel_hi:[0,0,0]
	v_mfma_scale_f32_16x16x128_f8f6f4 v[224:227], v[168:175], v[64:71], v[44:47], v143, v143 op_sel_hi:[0,0,0]
	v_mfma_scale_f32_16x16x128_f8f6f4 v[228:231], v[160:167], v[72:79], v[36:39], v143, v143 op_sel_hi:[0,0,0]
	v_mfma_scale_f32_16x16x128_f8f6f4 v[232:235], v[168:175], v[72:79], v[28:31], v143, v143 op_sel_hi:[0,0,0]
	v_mfma_scale_f32_16x16x128_f8f6f4 v[236:239], v[160:167], v[80:87], v[20:23], v143, v143 op_sel_hi:[0,0,0]
	v_mfma_scale_f32_16x16x128_f8f6f4 v[240:243], v[168:175], v[80:87], v[12:15], v143, v143 op_sel_hi:[0,0,0]
	v_mfma_scale_f32_16x16x128_f8f6f4 v[244:247], v[160:167], v[88:95], v[4:7], v143, v143 op_sel_hi:[0,0,0]
	v_mfma_scale_f32_16x16x128_f8f6f4 v[248:251], v[168:175], v[88:95], v[0:3], v143, v143 op_sel_hi:[0,0,0]
	s_setprio 0
	s_waitcnt vmcnt(8)
	s_barrier
	s_add_i32 s63, 0, 0x18000
	s_add_i32 s64, 0, 0x1c000
	s_nop 0
	v_add_u32_e32 v12, s63, v139
	v_add_u32_e32 v16, s64, v139
	ds_read_b128 v[0:3], v12
	ds_read_b128 v[4:7], v12 offset:1024
	ds_read_b128 v[8:11], v12 offset:2048
	ds_read_b128 v[12:15], v12 offset:3072
	ds_read_b128 v[144:147], v16
	ds_read_b128 v[148:151], v16 offset:1024
	ds_read_b128 v[152:155], v16 offset:2048
	ds_read_b128 v[156:159], v16 offset:3072
	s_add_u32 s54, s30, 0x40000
	v_mov_b32_e32 v64, v135
	v_mov_b32_e32 v65, v136
	s_addc_u32 s55, s31, 0
	s_mov_b32 m0, s42
	ds_read_b128 v[16:19], v142 offset:32768
	ds_read_b128 v[20:23], v142 offset:33792
	ds_read_b128 v[24:27], v142 offset:34816
	ds_read_b128 v[28:31], v142 offset:35840
	ds_read_b128 v[32:35], v142 offset:36864
	ds_read_b128 v[36:39], v142 offset:37888
	ds_read_b128 v[40:43], v142 offset:38912
	ds_read_b128 v[44:47], v142 offset:39936
	s_nop 0
	global_load_lds_dwordx4 v64, s[54:55]
	s_mov_b32 m0, s43
	s_nop 0
	global_load_lds_dwordx4 v65, s[54:55]
	s_and_b64 vcc, exec, s[14:15]
	s_cbranch_vccnz .Lmy_lw_35
	s_waitcnt vmcnt(8)
.Lmy_lw_35:
	s_waitcnt lgkmcnt(0)
	s_barrier
	s_setprio 1
	s_waitcnt lgkmcnt(0)
	v_mfma_scale_f32_16x16x128_f8f6f4 v[124:127], v[0:7], v[16:23], v[124:127], v143, v143 op_sel_hi:[0,0,0]
	v_mfma_scale_f32_16x16x128_f8f6f4 v[120:123], v[8:15], v[16:23], v[120:123], v143, v143 op_sel_hi:[0,0,0]
	v_mfma_scale_f32_16x16x128_f8f6f4 v[112:115], v[0:7], v[24:31], v[112:115], v143, v143 op_sel_hi:[0,0,0]
	v_mfma_scale_f32_16x16x128_f8f6f4 v[104:107], v[8:15], v[24:31], v[104:107], v143, v143 op_sel_hi:[0,0,0]
	v_mfma_scale_f32_16x16x128_f8f6f4 v[96:99], v[0:7], v[32:39], v[96:99], v143, v143 op_sel_hi:[0,0,0]
	v_mfma_scale_f32_16x16x128_f8f6f4 v[88:91], v[8:15], v[32:39], v[130:133], v143, v143 op_sel_hi:[0,0,0]
	v_mfma_scale_f32_16x16x128_f8f6f4 v[80:83], v[0:7], v[40:47], v[208:211], v143, v143 op_sel_hi:[0,0,0]
	v_mfma_scale_f32_16x16x128_f8f6f4 v[72:75], v[8:15], v[40:47], v[212:215], v143, v143 op_sel_hi:[0,0,0]
	s_setprio 0
	s_setprio 1
	v_mfma_scale_f32_16x16x128_f8f6f4 v[116:119], v[144:151], v[16:23], v[116:119], v143, v143 op_sel_hi:[0,0,0]
	v_mfma_scale_f32_16x16x128_f8f6f4 v[108:111], v[152:159], v[16:23], v[108:111], v143, v143 op_sel_hi:[0,0,0]
	v_mfma_scale_f32_16x16x128_f8f6f4 v[100:103], v[144:151], v[24:31], v[100:103], v143, v143 op_sel_hi:[0,0,0]
	v_mfma_scale_f32_16x16x128_f8f6f4 v[92:95], v[152:159], v[24:31], v[176:179], v143, v143 op_sel_hi:[0,0,0]
	v_mfma_scale_f32_16x16x128_f8f6f4 v[84:87], v[144:151], v[32:39], v[180:183], v143, v143 op_sel_hi:[0,0,0]
	v_mfma_scale_f32_16x16x128_f8f6f4 v[76:79], v[152:159], v[32:39], v[184:187], v143, v143 op_sel_hi:[0,0,0]
	v_mfma_scale_f32_16x16x128_f8f6f4 v[68:71], v[144:151], v[40:47], v[188:191], v143, v143 op_sel_hi:[0,0,0]
	v_mfma_scale_f32_16x16x128_f8f6f4 v[64:67], v[152:159], v[40:47], v[192:195], v143, v143 op_sel_hi:[0,0,0]
	s_setprio 0
	s_waitcnt vmcnt(8)
	s_barrier
	s_add_u32 s54, s34, 0x40000
	s_addc_u32 s55, s35, 0
	s_add_i32 s63, s63, s3
	v_mov_b32_e32 v16, v137
	v_mov_b32_e32 v17, v138
	s_mov_b32 m0, s63
	ds_read_b128 v[160:163], v142 offset:49152
	ds_read_b128 v[164:167], v142 offset:50176
	ds_read_b128 v[168:171], v142 offset:51200
	ds_read_b128 v[172:175], v142 offset:52224
	ds_read_b128 v[176:179], v142 offset:53248
	ds_read_b128 v[180:183], v142 offset:54272
	ds_read_b128 v[184:187], v142 offset:55296
	ds_read_b128 v[188:191], v142 offset:56320
	v_mov_b32_e32 v128, v135
	global_load_lds_dwordx4 v16, s[54:55]
	s_add_i32 m0, s63, 0x2000
	s_add_u32 s34, s34, 0x40800
	global_load_lds_dwordx4 v17, s[54:55]
	v_mov_b32_e32 v16, v137
	v_mov_b32_e32 v17, v138
	s_addc_u32 s35, s35, 0
	s_add_i32 s54, s64, s3
	s_mov_b32 m0, s54
	s_nop 0
	global_load_lds_dwordx4 v16, s[34:35]
	s_add_i32 m0, s54, 0x2000
	v_mov_b32_e32 v16, v136
	global_load_lds_dwordx4 v17, s[34:35]
	v_mov_b32_e32 v17, v129
	v_lshl_add_u64 v[18:19], s[30:31], 0, v[128:129]
	v_lshl_add_u64 v[18:19], v[18:19], 0, s[12:13]
	s_mov_b32 m0, s46
	v_lshl_add_u64 v[16:17], s[30:31], 0, v[16:17]
	global_load_lds_dwordx4 v[18:19], off
	v_lshl_add_u64 v[16:17], v[16:17], 0, s[12:13]
	s_mov_b32 m0, s47
	s_nop 0
	global_load_lds_dwordx4 v[16:17], off
	s_and_b64 vcc, exec, s[14:15]
	s_cbranch_vccnz .Lmy_lw_36
	s_waitcnt vmcnt(8)
.Lmy_lw_36:
	s_waitcnt lgkmcnt(0)
	s_barrier
	s_setprio 1
	s_waitcnt lgkmcnt(0)
	v_mfma_scale_f32_16x16x128_f8f6f4 v[60:63], v[0:7], v[160:167], v[60:63], v143, v143 op_sel_hi:[0,0,0]
	v_mfma_scale_f32_16x16x128_f8f6f4 v[56:59], v[8:15], v[160:167], v[56:59], v143, v143 op_sel_hi:[0,0,0]
	v_mfma_scale_f32_16x16x128_f8f6f4 v[48:51], v[0:7], v[168:175], v[48:51], v143, v143 op_sel_hi:[0,0,0]
	v_mfma_scale_f32_16x16x128_f8f6f4 v[40:43], v[8:15], v[168:175], v[196:199], v143, v143 op_sel_hi:[0,0,0]
	v_mfma_scale_f32_16x16x128_f8f6f4 v[32:35], v[0:7], v[176:183], v[200:203], v143, v143 op_sel_hi:[0,0,0]
	v_mfma_scale_f32_16x16x128_f8f6f4 v[24:27], v[8:15], v[176:183], v[204:207], v143, v143 op_sel_hi:[0,0,0]
	v_mfma_scale_f32_16x16x128_f8f6f4 v[16:19], v[0:7], v[184:191], v[216:219], v143, v143 op_sel_hi:[0,0,0]
	v_mfma_scale_f32_16x16x128_f8f6f4 v[8:11], v[8:15], v[184:191], v[220:223], v143, v143 op_sel_hi:[0,0,0]
	s_setprio 0
	s_setprio 1
	v_mfma_scale_f32_16x16x128_f8f6f4 v[52:55], v[144:151], v[160:167], v[52:55], v143, v143 op_sel_hi:[0,0,0]
	v_mfma_scale_f32_16x16x128_f8f6f4 v[44:47], v[152:159], v[160:167], v[224:227], v143, v143 op_sel_hi:[0,0,0]
	v_mfma_scale_f32_16x16x128_f8f6f4 v[36:39], v[144:151], v[168:175], v[228:231], v143, v143 op_sel_hi:[0,0,0]
	v_mfma_scale_f32_16x16x128_f8f6f4 v[28:31], v[152:159], v[168:175], v[232:235], v143, v143 op_sel_hi:[0,0,0]
	v_mfma_scale_f32_16x16x128_f8f6f4 v[20:23], v[144:151], v[176:183], v[236:239], v143, v143 op_sel_hi:[0,0,0]
	v_mfma_scale_f32_16x16x128_f8f6f4 v[12:15], v[152:159], v[176:183], v[240:243], v143, v143 op_sel_hi:[0,0,0]
	v_mfma_scale_f32_16x16x128_f8f6f4 v[4:7], v[144:151], v[184:191], v[244:247], v143, v143 op_sel_hi:[0,0,0]
	v_mfma_scale_f32_16x16x128_f8f6f4 v[0:3], v[152:159], v[184:191], v[248:251], v143, v143 op_sel_hi:[0,0,0]
	s_setprio 0
	s_waitcnt vmcnt(8)
	s_barrier
	s_add_i32 s53, s53, 2
	s_add_u32 s19, s19, 0x80000
	s_addc_u32 s52, s52, 0
	s_add_u32 s28, s28, 0x100
	s_addc_u32 s29, s29, 0
	s_cmp_gt_u32 s53, 13
	s_cbranch_scc0 .LBB0_2964
	s_and_b64 vcc, exec, s[14:15]
	s_cbranch_vccz .LBB0_2967
	s_barrier
